# all 16-byte global stores inside the layer loop made write-through (sc1) (on top of v18)
# baseline (speedup 1.0000x reference)
.LBB0_192:
	s_add_i32 s14, s2, 0xffffc000
	s_cmpk_lt_i32 s2, 0x4000
	s_cselect_b64 s[0:1], -1, 0
	s_and_b64 vcc, s[0:1], exec
	s_cselect_b32 s1, s3, 0
	s_cselect_b32 s0, s2, s14
	s_cselect_b32 s4, s79, s97
	s_cselect_b32 s5, s78, s96
	s_lshl_b64 s[0:1], s[0:1], 12
	s_add_u32 s0, s5, s0
	s_addc_u32 s1, s4, s1
	v_lshlrev_b32_e32 v56, 2, v34
	global_load_dwordx4 v[30:33], v56, s[0:1]
	global_load_dwordx4 v[26:29], v56, s[0:1] offset:1024
	global_load_dwordx4 v[22:25], v56, s[0:1] offset:2048
	global_load_dwordx4 v[18:21], v56, s[0:1] offset:3072
	s_cbranch_vccnz .LBB0_191
	s_lshl_b64 s[4:5], s[14:15], 12
	v_lshl_add_u64 v[42:43], v[36:37], 0, s[4:5]
	s_mov_b64 s[6:7], 0
	global_load_dwordx4 v[58:61], v[42:43], off
	global_load_dwordx4 v[62:65], v[42:43], off offset:1024
	global_load_dwordx4 v[66:69], v[42:43], off offset:2048
	global_load_dwordx4 v[70:73], v[42:43], off offset:3072
	s_add_u32 s6, s6, 0x200000
	v_lshl_add_u64 v[44:45], v[42:43], 0, s[6:7]
	global_load_dwordx4 v[74:77], v[44:45], off
	global_load_dwordx4 v[78:81], v[44:45], off offset:1024
	global_load_dwordx4 v[82:85], v[44:45], off offset:2048
	global_load_dwordx4 v[86:89], v[44:45], off offset:3072
	s_add_u32 s6, s6, 0x200000
	v_lshl_add_u64 v[44:45], v[42:43], 0, s[6:7]
	global_load_dwordx4 v[90:93], v[44:45], off
	global_load_dwordx4 v[94:97], v[44:45], off offset:1024
	global_load_dwordx4 v[98:101], v[44:45], off offset:2048
	global_load_dwordx4 v[102:105], v[44:45], off offset:3072
	s_add_u32 s6, s6, 0x200000
	v_lshl_add_u64 v[44:45], v[42:43], 0, s[6:7]
	global_load_dwordx4 v[106:109], v[44:45], off
	global_load_dwordx4 v[110:113], v[44:45], off offset:1024
	global_load_dwordx4 v[114:117], v[44:45], off offset:2048
	global_load_dwordx4 v[118:121], v[44:45], off offset:3072
	s_add_u32 s6, s6, 0x200000
	v_lshl_add_u64 v[44:45], v[42:43], 0, s[6:7]
	global_load_dwordx4 v[122:125], v[44:45], off
	global_load_dwordx4 v[126:129], v[44:45], off offset:1024
	global_load_dwordx4 v[130:133], v[44:45], off offset:2048
	global_load_dwordx4 v[134:137], v[44:45], off offset:3072
	s_add_u32 s6, s6, 0x200000
	v_lshl_add_u64 v[44:45], v[42:43], 0, s[6:7]
	global_load_dwordx4 v[138:141], v[44:45], off
	global_load_dwordx4 v[142:145], v[44:45], off offset:1024
	global_load_dwordx4 v[146:149], v[44:45], off offset:2048
	global_load_dwordx4 v[150:153], v[44:45], off offset:3072
	s_add_u32 s6, s6, 0x200000
	v_lshl_add_u64 v[44:45], v[42:43], 0, s[6:7]
	global_load_dwordx4 v[154:157], v[44:45], off
	global_load_dwordx4 v[158:161], v[44:45], off offset:1024
	global_load_dwordx4 v[162:165], v[44:45], off offset:2048
	global_load_dwordx4 v[166:169], v[44:45], off offset:3072
	s_add_u32 s6, s6, 0x200000
	v_lshl_add_u64 v[44:45], v[42:43], 0, s[6:7]
	global_load_dwordx4 v[170:173], v[44:45], off
	global_load_dwordx4 v[174:177], v[44:45], off offset:1024
	global_load_dwordx4 v[178:181], v[44:45], off offset:2048
	global_load_dwordx4 v[182:185], v[44:45], off offset:3072
	s_add_u32 s6, s6, 0x200000
	v_lshl_add_u64 v[44:45], v[42:43], 0, s[6:7]
	global_load_dwordx4 v[186:189], v[44:45], off
	global_load_dwordx4 v[190:193], v[44:45], off offset:1024
	global_load_dwordx4 v[194:197], v[44:45], off offset:2048
	global_load_dwordx4 v[214:217], v[44:45], off offset:3072
	s_add_u32 s6, s6, 0x200000
	v_lshl_add_u64 v[44:45], v[42:43], 0, s[6:7]
	global_load_dwordx4 v[218:221], v[44:45], off
	global_load_dwordx4 v[222:225], v[44:45], off offset:1024
	global_load_dwordx4 v[226:229], v[44:45], off offset:2048
	global_load_dwordx4 v[230:233], v[44:45], off offset:3072
	s_waitcnt vmcnt(39)
	v_pk_add_f32 v[32:33], v[32:33], v[60:61]
	v_pk_add_f32 v[30:31], v[30:31], v[58:59]
	s_add_u32 s6, s6, 0x200000
	v_lshl_add_u64 v[44:45], v[42:43], 0, s[6:7]
	global_load_dwordx4 v[58:61], v[44:45], off
	s_waitcnt vmcnt(39)
	v_pk_add_f32 v[28:29], v[28:29], v[64:65]
	v_pk_add_f32 v[26:27], v[26:27], v[62:63]
	global_load_dwordx4 v[62:65], v[44:45], off offset:1024
	s_waitcnt vmcnt(39)
	v_pk_add_f32 v[24:25], v[24:25], v[68:69]
	v_pk_add_f32 v[22:23], v[22:23], v[66:67]
	global_load_dwordx4 v[66:69], v[44:45], off offset:2048
	s_waitcnt vmcnt(39)
	v_pk_add_f32 v[20:21], v[20:21], v[72:73]
	v_pk_add_f32 v[18:19], v[18:19], v[70:71]
	global_load_dwordx4 v[70:73], v[44:45], off offset:3072
	s_waitcnt vmcnt(39)
	v_pk_add_f32 v[32:33], v[32:33], v[76:77]
	v_pk_add_f32 v[30:31], v[30:31], v[74:75]
	s_waitcnt vmcnt(38)
	v_pk_add_f32 v[28:29], v[28:29], v[80:81]
	v_pk_add_f32 v[26:27], v[26:27], v[78:79]
	s_waitcnt vmcnt(37)
	v_pk_add_f32 v[24:25], v[24:25], v[84:85]
	v_pk_add_f32 v[22:23], v[22:23], v[82:83]
	s_waitcnt vmcnt(36)
	v_pk_add_f32 v[20:21], v[20:21], v[88:89]
	v_pk_add_f32 v[18:19], v[18:19], v[86:87]
	s_waitcnt vmcnt(35)
	v_pk_add_f32 v[32:33], v[32:33], v[92:93]
	v_pk_add_f32 v[30:31], v[30:31], v[90:91]
	s_waitcnt vmcnt(34)
	v_pk_add_f32 v[28:29], v[28:29], v[96:97]
	v_pk_add_f32 v[26:27], v[26:27], v[94:95]
	s_waitcnt vmcnt(33)
	v_pk_add_f32 v[24:25], v[24:25], v[100:101]
	v_pk_add_f32 v[22:23], v[22:23], v[98:99]
	s_waitcnt vmcnt(32)
	v_pk_add_f32 v[20:21], v[20:21], v[104:105]
	v_pk_add_f32 v[18:19], v[18:19], v[102:103]
	s_waitcnt vmcnt(31)
	v_pk_add_f32 v[32:33], v[32:33], v[108:109]
	v_pk_add_f32 v[30:31], v[30:31], v[106:107]
	s_waitcnt vmcnt(30)
	v_pk_add_f32 v[28:29], v[28:29], v[112:113]
	v_pk_add_f32 v[26:27], v[26:27], v[110:111]
	s_waitcnt vmcnt(29)
	v_pk_add_f32 v[24:25], v[24:25], v[116:117]
	v_pk_add_f32 v[22:23], v[22:23], v[114:115]
	s_waitcnt vmcnt(28)
	v_pk_add_f32 v[20:21], v[20:21], v[120:121]
	v_pk_add_f32 v[18:19], v[18:19], v[118:119]
	s_waitcnt vmcnt(27)
	v_pk_add_f32 v[32:33], v[32:33], v[124:125]
	v_pk_add_f32 v[30:31], v[30:31], v[122:123]
	s_waitcnt vmcnt(26)
	v_pk_add_f32 v[28:29], v[28:29], v[128:129]
	v_pk_add_f32 v[26:27], v[26:27], v[126:127]
	s_waitcnt vmcnt(25)
	v_pk_add_f32 v[24:25], v[24:25], v[132:133]
	v_pk_add_f32 v[22:23], v[22:23], v[130:131]
	s_waitcnt vmcnt(24)
	v_pk_add_f32 v[20:21], v[20:21], v[136:137]
	v_pk_add_f32 v[18:19], v[18:19], v[134:135]
	s_waitcnt vmcnt(23)
	v_pk_add_f32 v[32:33], v[32:33], v[140:141]
	v_pk_add_f32 v[30:31], v[30:31], v[138:139]
	s_waitcnt vmcnt(22)
	v_pk_add_f32 v[28:29], v[28:29], v[144:145]
	v_pk_add_f32 v[26:27], v[26:27], v[142:143]
	s_waitcnt vmcnt(21)
	v_pk_add_f32 v[24:25], v[24:25], v[148:149]
	v_pk_add_f32 v[22:23], v[22:23], v[146:147]
	s_waitcnt vmcnt(20)
	v_pk_add_f32 v[20:21], v[20:21], v[152:153]
	v_pk_add_f32 v[18:19], v[18:19], v[150:151]
	s_waitcnt vmcnt(19)
	v_pk_add_f32 v[32:33], v[32:33], v[156:157]
	v_pk_add_f32 v[30:31], v[30:31], v[154:155]
	s_waitcnt vmcnt(18)
	v_pk_add_f32 v[28:29], v[28:29], v[160:161]
	v_pk_add_f32 v[26:27], v[26:27], v[158:159]
	s_waitcnt vmcnt(17)
	v_pk_add_f32 v[24:25], v[24:25], v[164:165]
	v_pk_add_f32 v[22:23], v[22:23], v[162:163]
	s_waitcnt vmcnt(16)
	v_pk_add_f32 v[20:21], v[20:21], v[168:169]
	v_pk_add_f32 v[18:19], v[18:19], v[166:167]
	s_waitcnt vmcnt(15)
	v_pk_add_f32 v[32:33], v[32:33], v[172:173]
	v_pk_add_f32 v[30:31], v[30:31], v[170:171]
	s_waitcnt vmcnt(14)
	v_pk_add_f32 v[28:29], v[28:29], v[176:177]
	v_pk_add_f32 v[26:27], v[26:27], v[174:175]
	s_waitcnt vmcnt(13)
	v_pk_add_f32 v[24:25], v[24:25], v[180:181]
	v_pk_add_f32 v[22:23], v[22:23], v[178:179]
	s_waitcnt vmcnt(12)
	v_pk_add_f32 v[20:21], v[20:21], v[184:185]
	v_pk_add_f32 v[18:19], v[18:19], v[182:183]
	s_waitcnt vmcnt(11)
	v_pk_add_f32 v[32:33], v[32:33], v[188:189]
	v_pk_add_f32 v[30:31], v[30:31], v[186:187]
	s_waitcnt vmcnt(10)
	v_pk_add_f32 v[28:29], v[28:29], v[192:193]
	v_pk_add_f32 v[26:27], v[26:27], v[190:191]
	s_waitcnt vmcnt(9)
	v_pk_add_f32 v[24:25], v[24:25], v[196:197]
	v_pk_add_f32 v[22:23], v[22:23], v[194:195]
	s_waitcnt vmcnt(8)
	v_pk_add_f32 v[20:21], v[20:21], v[216:217]
	v_pk_add_f32 v[18:19], v[18:19], v[214:215]
	s_waitcnt vmcnt(7)
	v_pk_add_f32 v[32:33], v[32:33], v[220:221]
	v_pk_add_f32 v[30:31], v[30:31], v[218:219]
	s_waitcnt vmcnt(6)
	v_pk_add_f32 v[28:29], v[28:29], v[224:225]
	v_pk_add_f32 v[26:27], v[26:27], v[222:223]
	s_waitcnt vmcnt(5)
	v_pk_add_f32 v[24:25], v[24:25], v[228:229]
	v_pk_add_f32 v[22:23], v[22:23], v[226:227]
	s_waitcnt vmcnt(4)
	v_pk_add_f32 v[20:21], v[20:21], v[232:233]
	v_pk_add_f32 v[18:19], v[18:19], v[230:231]
	s_waitcnt vmcnt(3)
	v_pk_add_f32 v[32:33], v[32:33], v[60:61]
	v_pk_add_f32 v[30:31], v[30:31], v[58:59]
	s_waitcnt vmcnt(2)
	v_pk_add_f32 v[28:29], v[28:29], v[64:65]
	v_pk_add_f32 v[26:27], v[26:27], v[62:63]
	s_waitcnt vmcnt(1)
	v_pk_add_f32 v[24:25], v[24:25], v[68:69]
	v_pk_add_f32 v[22:23], v[22:23], v[66:67]
	s_waitcnt vmcnt(0)
	v_pk_add_f32 v[20:21], v[20:21], v[72:73]
	v_pk_add_f32 v[18:19], v[18:19], v[70:71]
	v_lshl_add_u64 v[42:43], v[38:39], 0, s[4:5]
	global_store_dwordx4 v[42:43], v[30:33], off sc1
	global_store_dwordx4 v[42:43], v[26:29], off offset:1024 sc1
	global_store_dwordx4 v[42:43], v[22:25], off offset:2048 sc1
	global_store_dwordx4 v[42:43], v[18:21], off offset:3072 sc1
	s_branch .LBB0_191

.LBB0_262:
	v_readlane_b32 s0, v250, 13
	v_lshl_or_b32 v142, s35, 8, v146
	v_readlane_b32 s1, v250, 14
	v_lshl_add_u32 v150, s36, 8, v144
	v_ashrrev_i32_e32 v143, 31, v142
	v_mov_b64_e32 v[140:141], s[0:1]
	s_movk_i32 s7, 0x1200
	v_mad_i64_i32 v[148:149], s[0:1], v150, s7, v[140:141]
	v_lshlrev_b64 v[142:143], 1, v[142:143]
	v_lshl_add_u64 v[148:149], v[148:149], 0, v[142:143]
	v_cvt_pk_bf16_f32 v126, v126, v127
	v_cvt_pk_bf16_f32 v127, v128, v129
	v_cvt_pk_bf16_f32 v128, v122, v123
	v_cvt_pk_bf16_f32 v129, v124, v125
	global_store_dwordx4 v[148:149], v[126:129], off sc1
	v_cvt_pk_bf16_f32 v114, v114, v115
	v_cvt_pk_bf16_f32 v115, v116, v117
	v_cvt_pk_bf16_f32 v116, v106, v107
	v_or_b32_e32 v106, 16, v150
	v_mad_i64_i32 v[106:107], s[0:1], v106, s7, v[140:141]
	v_cvt_pk_bf16_f32 v117, v108, v109
	global_store_dwordx4 v[148:149], v[114:117], off offset:256 sc1
	s_andn2_b64 vcc, exec, s[38:39]
	s_nop 0
	v_lshl_add_u64 v[114:115], v[106:107], 0, v[142:143]
	v_cvt_pk_bf16_f32 v106, v118, v119
	v_cvt_pk_bf16_f32 v107, v120, v121
	v_cvt_pk_bf16_f32 v108, v110, v111
	v_cvt_pk_bf16_f32 v109, v112, v113
	global_store_dwordx4 v[114:115], v[106:109], off sc1
	v_cvt_pk_bf16_f32 v98, v98, v99
	v_cvt_pk_bf16_f32 v99, v100, v101
	v_cvt_pk_bf16_f32 v100, v90, v91
	v_or_b32_e32 v90, 32, v150
	v_mad_i64_i32 v[90:91], s[0:1], v90, s7, v[140:141]
	v_cvt_pk_bf16_f32 v101, v92, v93
	global_store_dwordx4 v[114:115], v[98:101], off offset:256 sc1
	s_nop 1
	v_lshl_add_u64 v[98:99], v[90:91], 0, v[142:143]
	v_cvt_pk_bf16_f32 v90, v102, v103
	v_cvt_pk_bf16_f32 v91, v104, v105
	v_cvt_pk_bf16_f32 v92, v94, v95
	v_cvt_pk_bf16_f32 v93, v96, v97
	global_store_dwordx4 v[98:99], v[90:93], off sc1
	v_cvt_pk_bf16_f32 v82, v82, v83
	v_cvt_pk_bf16_f32 v83, v84, v85
	v_cvt_pk_bf16_f32 v84, v74, v75
	v_or_b32_e32 v74, 48, v150
	v_mad_i64_i32 v[74:75], s[0:1], v74, s7, v[140:141]
	v_cvt_pk_bf16_f32 v85, v76, v77
	global_store_dwordx4 v[98:99], v[82:85], off offset:256 sc1
	s_nop 1
	v_lshl_add_u64 v[82:83], v[74:75], 0, v[142:143]
	v_cvt_pk_bf16_f32 v74, v86, v87
	v_cvt_pk_bf16_f32 v75, v88, v89
	v_cvt_pk_bf16_f32 v76, v78, v79
	v_cvt_pk_bf16_f32 v77, v80, v81
	global_store_dwordx4 v[82:83], v[74:77], off sc1
	v_cvt_pk_bf16_f32 v70, v70, v71
	v_cvt_pk_bf16_f32 v71, v72, v73
	v_cvt_pk_bf16_f32 v72, v66, v67
	v_add_u32_e32 v66, 0x80, v150
	v_mad_i64_i32 v[66:67], s[0:1], v66, s7, v[140:141]
	v_lshl_add_u64 v[66:67], v[66:67], 0, v[142:143]
	v_cvt_pk_bf16_f32 v73, v68, v69
	global_store_dwordx4 v[82:83], v[70:73], off offset:256 sc1
	v_cvt_pk_bf16_f32 v62, v62, v63
	v_cvt_pk_bf16_f32 v63, v64, v65
	v_cvt_pk_bf16_f32 v64, v58, v59
	v_cvt_pk_bf16_f32 v65, v60, v61
	global_store_dwordx4 v[66:67], v[62:65], off sc1
	v_cvt_pk_bf16_f32 v50, v50, v51
	v_cvt_pk_bf16_f32 v51, v52, v53
	v_cvt_pk_bf16_f32 v52, v42, v43
	v_add_u32_e32 v42, 0x90, v150
	v_mad_i64_i32 v[42:43], s[0:1], v42, s7, v[140:141]
	v_cvt_pk_bf16_f32 v53, v44, v45
	global_store_dwordx4 v[66:67], v[50:53], off offset:256 sc1
	s_nop 1
	v_lshl_add_u64 v[50:51], v[42:43], 0, v[142:143]
	v_cvt_pk_bf16_f32 v42, v54, v55
	v_cvt_pk_bf16_f32 v43, v56, v57
	v_cvt_pk_bf16_f32 v44, v46, v47
	v_cvt_pk_bf16_f32 v45, v48, v49
	global_store_dwordx4 v[50:51], v[42:45], off sc1
	v_cvt_pk_bf16_f32 v34, v34, v35
	v_cvt_pk_bf16_f32 v35, v36, v37
	v_cvt_pk_bf16_f32 v36, v26, v27
	v_add_u32_e32 v26, 0xa0, v150
	v_mad_i64_i32 v[26:27], s[0:1], v26, s7, v[140:141]
	v_cvt_pk_bf16_f32 v37, v28, v29
	global_store_dwordx4 v[50:51], v[34:37], off offset:256 sc1
	s_nop 1
	v_lshl_add_u64 v[34:35], v[26:27], 0, v[142:143]
	v_cvt_pk_bf16_f32 v26, v38, v39
	v_cvt_pk_bf16_f32 v27, v40, v41
	v_cvt_pk_bf16_f32 v28, v30, v31
	v_cvt_pk_bf16_f32 v29, v32, v33
	global_store_dwordx4 v[34:35], v[26:29], off sc1
	v_cvt_pk_bf16_f32 v18, v18, v19
	v_cvt_pk_bf16_f32 v19, v20, v21
	v_cvt_pk_bf16_f32 v20, v10, v11
	v_add_u32_e32 v10, 0xb0, v150
	v_mad_i64_i32 v[10:11], s[0:1], v10, s7, v[140:141]
	v_cvt_pk_bf16_f32 v21, v12, v13
	global_store_dwordx4 v[34:35], v[18:21], off offset:256 sc1
	s_mov_b64 s[0:1], -1
	s_nop 0
	v_lshl_add_u64 v[18:19], v[10:11], 0, v[142:143]
	v_cvt_pk_bf16_f32 v10, v22, v23
	v_cvt_pk_bf16_f32 v11, v24, v25
	v_cvt_pk_bf16_f32 v12, v14, v15
	v_cvt_pk_bf16_f32 v13, v16, v17
	global_store_dwordx4 v[18:19], v[10:13], off sc1
	v_cvt_pk_bf16_f32 v6, v6, v7
	v_cvt_pk_bf16_f32 v7, v8, v9
	v_cvt_pk_bf16_f32 v8, v2, v3
	v_cvt_pk_bf16_f32 v9, v4, v5
	global_store_dwordx4 v[18:19], v[6:9], off offset:256 sc1
	s_cbranch_vccnz .LBB0_251
	s_andn2_b64 vcc, exec, s[2:3]
	s_cbranch_vccnz .LBB0_250
	s_barrier
	s_branch .LBB0_250

.LBB0_334:
	s_or_b64 exec, exec, s[0:1]
	v_lshlrev_b32_e32 v130, 4, v130
	v_ashrrev_i32_e32 v131, 31, v130
	v_lshl_add_u64 v[138:139], v[130:131], 2, v[150:151]
	s_mov_b64 s[0:1], 0x2000
	v_lshl_add_u64 v[140:141], v[138:139], 0, s[0:1]
	s_movk_i32 s0, 0x2000
	global_load_dwordx4 v[134:137], v[138:139], off
	global_load_dwordx4 v[130:133], v[138:139], off offset:16
	v_add_co_u32_e32 v138, vcc, s0, v138
	s_waitcnt vmcnt(5)
	v_lshlrev_b32_e32 v164, 16, v146
	v_addc_co_u32_e32 v139, vcc, 0, v139, vcc
	global_load_dwordx4 v[142:145], v[138:139], off
	s_nop 0
	global_load_dwordx4 v[138:141], v[140:141], off offset:16
	v_and_b32_e32 v165, 0xffff0000, v146
	v_lshlrev_b32_e32 v160, 16, v147
	v_and_b32_e32 v161, 0xffff0000, v147
	v_pk_mul_f32 v[146:147], v[164:165], v[164:165]
	v_pk_mul_f32 v[162:163], v[160:161], v[160:161]
	v_add_f32_e32 v146, v146, v147
	v_lshlrev_b32_e32 v158, 16, v148
	v_and_b32_e32 v159, 0xffff0000, v148
	v_add_f32_e32 v146, v162, v146
	v_lshlrev_b32_e32 v154, 16, v149
	v_and_b32_e32 v155, 0xffff0000, v149
	v_pk_mul_f32 v[148:149], v[158:159], v[158:159]
	v_add_f32_e32 v146, v163, v146
	v_add_f32_e32 v146, v148, v146
	v_pk_mul_f32 v[156:157], v[154:155], v[154:155]
	v_add_f32_e32 v146, v149, v146
	v_add_f32_e32 v146, v156, v146
	v_add_f32_e32 v146, v157, v146
	ds_bpermute_b32 v147, v176, v146
	s_waitcnt lgkmcnt(0)
	v_add_f32_e32 v146, v146, v147
	ds_bpermute_b32 v147, v177, v146
	s_waitcnt lgkmcnt(0)
	v_add_f32_e32 v146, v146, v147
	ds_bpermute_b32 v147, v178, v146
	s_waitcnt lgkmcnt(0)
	v_add_f32_e32 v146, v146, v147
	v_fmamk_f32 v146, v146, 0x3c800000, v199
	v_cmp_gt_f32_e32 vcc, s21, v146
	v_mul_f32_e32 v147, 0x4f800000, v146
	s_nop 0
	v_cndmask_b32_e32 v146, v146, v147, vcc
	v_sqrt_f32_e32 v147, v146
	s_nop 0
	v_add_u32_e32 v148, -1, v147
	v_fma_f32 v149, -v148, v147, v146
	v_cmp_ge_f32_e64 s[50:51], 0, v149
	v_add_u32_e32 v149, 1, v147
	s_nop 0
	v_cndmask_b32_e64 v148, v147, v148, s[50:51]
	v_fma_f32 v147, -v149, v147, v146
	v_cmp_lt_f32_e64 s[50:51], 0, v147
	s_nop 1
	v_cndmask_b32_e64 v147, v148, v149, s[50:51]
	v_mul_f32_e32 v148, 0x37800000, v147
	v_cndmask_b32_e32 v147, v147, v148, vcc
	v_cmp_class_f32_e32 vcc, v146, v200
	s_nop 1
	v_cndmask_b32_e32 v146, v147, v146, vcc
	v_div_scale_f32 v147, s[0:1], v146, v146, 1.0
	v_rcp_f32_e32 v148, v147
	s_nop 0
	v_fma_f32 v149, -v147, v148, 1.0
	v_fmac_f32_e32 v148, v149, v148
	v_div_scale_f32 v149, vcc, 1.0, v146, 1.0
	v_mul_f32_e32 v156, v149, v148
	v_fma_f32 v157, -v147, v156, v149
	v_fmac_f32_e32 v156, v157, v148
	v_fma_f32 v147, -v147, v156, v149
	v_div_fmas_f32 v147, v147, v148, v156
	v_div_fixup_f32 v146, v147, v146, 1.0
	v_pk_mul_f32 v[148:149], v[146:147], v[164:165] op_sel_hi:[0,1]
	v_pk_mul_f32 v[148:149], v[14:15], v[148:149]
	v_pk_mul_f32 v[156:157], v[146:147], v[160:161] op_sel_hi:[0,1]
	v_pk_mul_f32 v[158:159], v[146:147], v[158:159] op_sel_hi:[0,1]
	v_pk_mul_f32 v[146:147], v[146:147], v[154:155] op_sel_hi:[0,1]
	ds_bpermute_b32 v154, v177, v148
	ds_bpermute_b32 v155, v177, v149
	v_pk_mul_f32 v[156:157], v[16:17], v[156:157]
	v_pk_mul_f32 v[158:159], v[10:11], v[158:159]
	v_pk_mul_f32 v[146:147], v[12:13], v[146:147]
	s_waitcnt vmcnt(1) lgkmcnt(0)
	v_pk_mul_f32 v[154:155], v[142:143], v[154:155]
	s_nop 0
	v_cndmask_b32_e64 v155, v155, -v155, s[44:45]
	v_cndmask_b32_e64 v154, v154, -v154, s[44:45]
	v_pk_fma_f32 v[148:149], v[134:135], v[148:149], v[154:155]
	ds_bpermute_b32 v154, v177, v156
	ds_bpermute_b32 v155, v177, v157
	v_pk_mul_f32 v[148:149], v[148:149], s[20:21] op_sel_hi:[1,0]
	s_waitcnt lgkmcnt(0)
	v_pk_mul_f32 v[154:155], v[144:145], v[154:155]
	s_nop 0
	v_cndmask_b32_e64 v155, v155, -v155, s[44:45]
	v_cndmask_b32_e64 v154, v154, -v154, s[44:45]
	v_pk_fma_f32 v[154:155], v[136:137], v[156:157], v[154:155]
	ds_bpermute_b32 v156, v177, v158
	ds_bpermute_b32 v157, v177, v159
	v_pk_mul_f32 v[154:155], v[154:155], s[20:21] op_sel_hi:[1,0]
	s_waitcnt vmcnt(0) lgkmcnt(0)
	v_pk_mul_f32 v[156:157], v[138:139], v[156:157]
	s_nop 0
	v_cndmask_b32_e64 v157, v157, -v157, s[44:45]
	v_cndmask_b32_e64 v156, v156, -v156, s[44:45]
	v_pk_fma_f32 v[156:157], v[130:131], v[158:159], v[156:157]
	ds_bpermute_b32 v158, v177, v146
	ds_bpermute_b32 v159, v177, v147
	v_pk_mul_f32 v[156:157], v[156:157], s[20:21] op_sel_hi:[1,0]
	s_waitcnt lgkmcnt(0)
	v_pk_mul_f32 v[158:159], v[140:141], v[158:159]
	s_nop 0
	v_cndmask_b32_e64 v159, v159, -v159, s[44:45]
	v_cndmask_b32_e64 v158, v158, -v158, s[44:45]
	v_pk_fma_f32 v[146:147], v[132:133], v[146:147], v[158:159]
	s_nop 0
	v_pk_mul_f32 v[158:159], v[146:147], s[20:21] op_sel_hi:[1,0]
	v_cvt_pk_bf16_f32 v146, v148, v149
	v_cvt_pk_bf16_f32 v147, v154, v155
	v_cvt_pk_bf16_f32 v148, v156, v157
	v_cvt_pk_bf16_f32 v149, v158, v159
	v_lshl_add_u64 v[154:155], s[10:11], 0, v[0:1]
	v_lshlrev_b32_e32 v156, 16, v126
	v_and_b32_e32 v157, 0xffff0000, v126
	global_store_dwordx4 v[154:155], v[146:149], off sc1
	v_lshlrev_b32_e32 v154, 16, v127
	v_and_b32_e32 v155, 0xffff0000, v127
	v_pk_mul_f32 v[164:165], v[156:157], v[156:157]
	v_pk_mul_f32 v[158:159], v[154:155], v[154:155]
	v_add_f32_e32 v164, v164, v165
	v_lshlrev_b32_e32 v148, 16, v128
	v_and_b32_e32 v149, 0xffff0000, v128
	v_add_f32_e32 v158, v158, v164
	v_pk_mul_f32 v[160:161], v[148:149], v[148:149]
	v_add_f32_e32 v158, v159, v158
	v_lshlrev_b32_e32 v146, 16, v129
	v_and_b32_e32 v147, 0xffff0000, v129
	v_add_f32_e32 v158, v160, v158
	v_pk_mul_f32 v[162:163], v[146:147], v[146:147]
	v_add_f32_e32 v158, v161, v158
	v_add_f32_e32 v158, v162, v158
	v_add_f32_e32 v158, v163, v158
	ds_bpermute_b32 v159, v176, v158
	s_waitcnt lgkmcnt(0)
	v_add_f32_e32 v158, v158, v159
	ds_bpermute_b32 v159, v177, v158
	s_waitcnt lgkmcnt(0)
	v_add_f32_e32 v158, v158, v159
	ds_bpermute_b32 v159, v178, v158
	s_waitcnt lgkmcnt(0)
	v_add_f32_e32 v158, v158, v159
	v_fmamk_f32 v158, v158, 0x3c800000, v199
	v_cmp_gt_f32_e32 vcc, s21, v158
	v_mul_f32_e32 v159, 0x4f800000, v158
	s_nop 0
	v_cndmask_b32_e32 v158, v158, v159, vcc
	v_sqrt_f32_e32 v159, v158
	s_nop 0
	v_add_u32_e32 v160, -1, v159
	v_fma_f32 v161, -v160, v159, v158
	v_cmp_ge_f32_e64 s[50:51], 0, v161
	v_add_u32_e32 v161, 1, v159
	s_nop 0
	v_cndmask_b32_e64 v160, v159, v160, s[50:51]
	v_fma_f32 v159, -v161, v159, v158
	v_cmp_lt_f32_e64 s[50:51], 0, v159
	s_nop 1
	v_cndmask_b32_e64 v159, v160, v161, s[50:51]
	v_mul_f32_e32 v160, 0x37800000, v159
	v_cndmask_b32_e32 v159, v159, v160, vcc
	v_cmp_class_f32_e32 vcc, v158, v200
	s_nop 1
	v_cndmask_b32_e32 v158, v159, v158, vcc
	v_div_scale_f32 v159, s[0:1], v158, v158, 1.0
	v_rcp_f32_e32 v160, v159
	s_nop 0
	v_fma_f32 v161, -v159, v160, 1.0
	v_fmac_f32_e32 v160, v161, v160
	v_div_scale_f32 v161, vcc, 1.0, v158, 1.0
	v_mul_f32_e32 v162, v161, v160
	v_fma_f32 v163, -v159, v162, v161
	v_fmac_f32_e32 v162, v163, v160
	v_fma_f32 v159, -v159, v162, v161
	v_div_fmas_f32 v159, v159, v160, v162
	v_div_fixup_f32 v158, v159, v158, 1.0
	v_pk_mul_f32 v[160:161], v[158:159], v[156:157] op_sel_hi:[0,1]
	v_pk_mul_f32 v[164:165], v[22:23], v[160:161]
	v_pk_mul_f32 v[160:161], v[158:159], v[154:155] op_sel_hi:[0,1]
	v_pk_mul_f32 v[162:163], v[24:25], v[160:161]
	v_pk_mul_f32 v[160:161], v[158:159], v[148:149] op_sel_hi:[0,1]
	v_pk_mul_f32 v[158:159], v[158:159], v[146:147] op_sel_hi:[0,1]
	v_pk_mul_f32 v[160:161], v[18:19], v[160:161]
	v_pk_mul_f32 v[158:159], v[20:21], v[158:159]
	ds_bpermute_b32 v172, v177, v164
	ds_bpermute_b32 v173, v177, v165
	ds_bpermute_b32 v170, v177, v162
	ds_bpermute_b32 v171, v177, v163
	ds_bpermute_b32 v168, v177, v160
	ds_bpermute_b32 v169, v177, v161
	ds_bpermute_b32 v166, v177, v158
	ds_bpermute_b32 v167, v177, v159
	s_and_saveexec_b64 s[0:1], s[46:47]
	s_xor_b64 s[0:1], exec, s[0:1]
	s_cbranch_execz .LBB0_338
	s_and_saveexec_b64 s[22:23], s[48:49]
	s_cbranch_execz .LBB0_337
	v_lshl_add_u64 v[130:131], s[4:5], 0, v[0:1]
	v_add_co_u32_e32 v130, vcc, 0x1326f000, v130
	s_nop 1
	v_addc_co_u32_e32 v131, vcc, 0, v131, vcc
	global_store_dwordx4 v[130:131], v[126:129], off offset:3840 sc1

.LBB0_338:
	s_andn2_saveexec_b64 s[0:1], s[0:1]
	s_cbranch_execz .LBB0_340
	s_waitcnt lgkmcnt(6)
	v_pk_mul_f32 v[126:127], v[142:143], v[172:173]
	s_waitcnt lgkmcnt(4)
	v_pk_mul_f32 v[128:129], v[144:145], v[170:171]
	v_cndmask_b32_e64 v127, v127, -v127, s[44:45]
	v_cndmask_b32_e64 v126, v126, -v126, s[44:45]
	v_pk_fma_f32 v[126:127], v[134:135], v[164:165], v[126:127]
	s_waitcnt lgkmcnt(2)
	v_pk_mul_f32 v[134:135], v[138:139], v[168:169]
	v_cndmask_b32_e64 v129, v129, -v129, s[44:45]
	v_cndmask_b32_e64 v128, v128, -v128, s[44:45]
	v_cndmask_b32_e64 v135, v135, -v135, s[44:45]
	v_cndmask_b32_e64 v134, v134, -v134, s[44:45]
	v_pk_fma_f32 v[128:129], v[136:137], v[162:163], v[128:129]
	v_pk_fma_f32 v[130:131], v[130:131], v[160:161], v[134:135]
	s_waitcnt lgkmcnt(0)
	v_pk_mul_f32 v[134:135], v[140:141], v[166:167]
	v_cvt_pk_bf16_f32 v126, v126, v127
	v_cndmask_b32_e64 v135, v135, -v135, s[44:45]
	v_cndmask_b32_e64 v134, v134, -v134, s[44:45]
	v_cvt_pk_bf16_f32 v127, v128, v129
	v_cvt_pk_bf16_f32 v128, v130, v131
	v_lshl_add_u64 v[130:131], s[4:5], 0, v[0:1]
	v_pk_fma_f32 v[132:133], v[132:133], v[158:159], v[134:135]
	v_add_co_u32_e32 v130, vcc, 0x12e50000, v130
	v_cvt_pk_bf16_f32 v129, v132, v133
	s_nop 0
	v_addc_co_u32_e32 v131, vcc, 0, v131, vcc
	global_store_dwordx4 v[130:131], v[126:129], off sc1
.LBB0_340:
	s_or_b64 exec, exec, s[0:1]
	s_nop 0
	v_lshlrev_b32_e32 v128, 16, v122
	v_and_b32_e32 v129, 0xffff0000, v122
	v_lshlrev_b32_e32 v122, 16, v123
	v_and_b32_e32 v123, 0xffff0000, v123
	v_pk_mul_f32 v[130:131], v[128:129], v[128:129]
	v_pk_mul_f32 v[132:133], v[122:123], v[122:123]
	v_add_f32_e32 v130, v130, v131
	v_lshlrev_b32_e32 v126, 16, v124
	v_and_b32_e32 v127, 0xffff0000, v124
	v_add_f32_e32 v130, v132, v130
	v_pk_mul_f32 v[134:135], v[126:127], v[126:127]
	v_add_f32_e32 v130, v133, v130
	v_lshlrev_b32_e32 v124, 16, v125
	v_and_b32_e32 v125, 0xffff0000, v125
	v_add_f32_e32 v130, v134, v130
	v_pk_mul_f32 v[136:137], v[124:125], v[124:125]
	v_add_f32_e32 v130, v135, v130
	v_add_f32_e32 v130, v136, v130
	v_add_f32_e32 v130, v137, v130
	s_and_saveexec_b64 s[0:1], s[40:41]
	s_xor_b64 s[0:1], exec, s[0:1]
	s_cbranch_execz .LBB0_342
	ds_bpermute_b32 v131, v176, v130
	s_waitcnt lgkmcnt(0)
	v_add_f32_e32 v130, v130, v131
	ds_bpermute_b32 v131, v177, v130
	s_waitcnt lgkmcnt(0)
	v_add_f32_e32 v130, v130, v131
	ds_bpermute_b32 v131, v178, v130
	s_waitcnt lgkmcnt(0)
	v_add_f32_e32 v130, v130, v131
	v_fmamk_f32 v130, v130, 0x3c800000, v199
	v_mul_f32_e32 v131, 0x4f800000, v130
	v_cmp_gt_f32_e32 vcc, s21, v130
	s_nop 1
	v_cndmask_b32_e32 v130, v130, v131, vcc
	v_sqrt_f32_e32 v131, v130
	s_nop 0
	v_add_u32_e32 v132, -1, v131
	v_add_u32_e32 v133, 1, v131
	v_fma_f32 v134, -v132, v131, v130
	v_fma_f32 v135, -v133, v131, v130
	v_cmp_ge_f32_e64 s[50:51], 0, v134
	s_nop 1
	v_cndmask_b32_e64 v131, v131, v132, s[50:51]
	v_cmp_lt_f32_e64 s[50:51], 0, v135
	s_nop 1
	v_cndmask_b32_e64 v131, v131, v133, s[50:51]
	v_mul_f32_e32 v132, 0x37800000, v131
	v_cndmask_b32_e32 v131, v131, v132, vcc
	v_cmp_class_f32_e32 vcc, v130, v200
	s_nop 1
	v_cndmask_b32_e32 v130, v131, v130, vcc
	v_div_scale_f32 v131, s[22:23], v130, v130, 1.0
	v_rcp_f32_e32 v132, v131
	v_div_scale_f32 v133, vcc, 1.0, v130, 1.0
	v_fma_f32 v134, -v131, v132, 1.0
	v_fmac_f32_e32 v132, v134, v132
	v_mul_f32_e32 v134, v133, v132
	v_fma_f32 v135, -v131, v134, v133
	v_fmac_f32_e32 v134, v135, v132
	v_fma_f32 v131, -v131, v134, v133
	v_div_fmas_f32 v131, v131, v132, v134
	v_div_fixup_f32 v130, v131, v130, 1.0
	v_pk_mul_f32 v[128:129], v[130:131], v[128:129] op_sel_hi:[0,1]
	v_pk_mul_f32 v[122:123], v[130:131], v[122:123] op_sel_hi:[0,1]
	v_pk_mul_f32 v[126:127], v[130:131], v[126:127] op_sel_hi:[0,1]
	v_pk_mul_f32 v[124:125], v[130:131], v[124:125] op_sel_hi:[0,1]
	v_pk_mul_f32 v[128:129], v[38:39], v[128:129]
	v_pk_mul_f32 v[130:131], v[40:41], v[122:123]
	v_pk_mul_f32 v[126:127], v[34:35], v[126:127]
	v_pk_mul_f32 v[132:133], v[36:37], v[124:125]
	v_cvt_pk_bf16_f32 v122, v128, v129
	v_cvt_pk_bf16_f32 v123, v130, v131
	v_cvt_pk_bf16_f32 v124, v126, v127
	v_cvt_pk_bf16_f32 v125, v132, v133
	v_lshl_add_u64 v[126:127], s[6:7], 0, v[0:1]
	global_store_dwordx4 v[126:127], v[122:125], off sc1
.LBB0_342:
	s_andn2_saveexec_b64 s[0:1], s[0:1]
	s_cbranch_execz .LBB0_344
	ds_bpermute_b32 v131, v176, v130
	s_waitcnt lgkmcnt(0)
	v_add_f32_e32 v130, v130, v131
	ds_bpermute_b32 v131, v177, v130
	s_waitcnt lgkmcnt(0)
	v_add_f32_e32 v130, v130, v131
	ds_bpermute_b32 v131, v178, v130
	s_waitcnt lgkmcnt(0)
	v_add_f32_e32 v130, v130, v131
	v_fmamk_f32 v130, v130, 0x3c800000, v199
	v_mul_f32_e32 v131, 0x4f800000, v130
	v_cmp_gt_f32_e32 vcc, s21, v130
	s_nop 1
	v_cndmask_b32_e32 v130, v130, v131, vcc
	v_sqrt_f32_e32 v131, v130
	s_nop 0
	v_add_u32_e32 v132, -1, v131
	v_add_u32_e32 v133, 1, v131
	v_fma_f32 v134, -v132, v131, v130
	v_fma_f32 v135, -v133, v131, v130
	v_cmp_ge_f32_e64 s[50:51], 0, v134
	s_nop 1
	v_cndmask_b32_e64 v131, v131, v132, s[50:51]
	v_cmp_lt_f32_e64 s[50:51], 0, v135
	s_nop 1
	v_cndmask_b32_e64 v131, v131, v133, s[50:51]
	v_mul_f32_e32 v132, 0x37800000, v131
	v_cndmask_b32_e32 v131, v131, v132, vcc
	v_cmp_class_f32_e32 vcc, v130, v200
	s_nop 1
	v_cndmask_b32_e32 v130, v131, v130, vcc
	v_div_scale_f32 v131, s[22:23], v130, v130, 1.0
	v_rcp_f32_e32 v132, v131
	v_div_scale_f32 v133, vcc, 1.0, v130, 1.0
	v_fma_f32 v134, -v131, v132, 1.0
	v_fmac_f32_e32 v132, v134, v132
	v_mul_f32_e32 v134, v133, v132
	v_fma_f32 v135, -v131, v134, v133
	v_fmac_f32_e32 v134, v135, v132
	v_fma_f32 v131, -v131, v134, v133
	v_div_fmas_f32 v131, v131, v132, v134
	v_div_fixup_f32 v130, v131, v130, 1.0
	v_pk_mul_f32 v[128:129], v[130:131], v[128:129] op_sel_hi:[0,1]
	v_pk_mul_f32 v[122:123], v[130:131], v[122:123] op_sel_hi:[0,1]
	v_pk_mul_f32 v[126:127], v[130:131], v[126:127] op_sel_hi:[0,1]
	v_pk_mul_f32 v[124:125], v[130:131], v[124:125] op_sel_hi:[0,1]
	v_pk_mul_f32 v[128:129], v[30:31], v[128:129]
	v_pk_mul_f32 v[122:123], v[32:33], v[122:123]
	v_pk_mul_f32 v[126:127], v[26:27], v[126:127]
	v_pk_mul_f32 v[124:125], v[28:29], v[124:125]
	v_pk_mul_f32 v[128:129], v[128:129], s[20:21] op_sel_hi:[1,0]
	v_pk_mul_f32 v[130:131], v[122:123], s[20:21] op_sel_hi:[1,0]
	v_pk_mul_f32 v[126:127], v[126:127], s[20:21] op_sel_hi:[1,0]
	v_pk_mul_f32 v[132:133], v[124:125], s[20:21] op_sel_hi:[1,0]
	v_cvt_pk_bf16_f32 v122, v128, v129
	v_cvt_pk_bf16_f32 v123, v130, v131
	v_cvt_pk_bf16_f32 v124, v126, v127
	v_cvt_pk_bf16_f32 v125, v132, v133
	v_lshl_add_u64 v[126:127], s[8:9], 0, v[0:1]
	global_store_dwordx4 v[126:127], v[122:125], off sc1

.LBB0_389:
	s_ashr_i32 s9, s8, 31
	v_pk_mul_f32 v[146:147], v[146:147], s[20:21] op_sel_hi:[1,0]
	v_pk_mul_f32 v[148:149], v[148:149], s[20:21] op_sel_hi:[1,0]
	v_pk_mul_f32 v[166:167], v[166:167], s[20:21] op_sel_hi:[1,0]
	v_pk_mul_f32 v[168:169], v[168:169], s[20:21] op_sel_hi:[1,0]
	s_lshl_b64 s[0:1], s[8:9], 10
	v_cvt_pk_bf16_f32 v146, v146, v147
	v_cvt_pk_bf16_f32 v147, v148, v149
	v_cvt_pk_bf16_f32 v148, v166, v167
	v_cvt_pk_bf16_f32 v149, v168, v169
	v_lshl_add_u64 v[166:167], v[154:155], 0, s[0:1]
	s_waitcnt vmcnt(6)
	v_lshlrev_b32_e32 v168, 16, v126
	v_and_b32_e32 v169, 0xffff0000, v126
	global_store_dwordx4 v[166:167], v[146:149], off sc1
	v_lshlrev_b32_e32 v166, 16, v127
	v_and_b32_e32 v167, 0xffff0000, v127
	v_pk_mul_f32 v[176:177], v[168:169], v[168:169]
	v_pk_mul_f32 v[170:171], v[166:167], v[166:167]
	v_add_f32_e32 v0, v176, v177
	v_lshlrev_b32_e32 v148, 16, v128
	v_and_b32_e32 v149, 0xffff0000, v128
	v_add_f32_e32 v0, v170, v0
	v_pk_mul_f32 v[172:173], v[148:149], v[148:149]
	v_add_f32_e32 v0, v171, v0
	v_lshlrev_b32_e32 v146, 16, v129
	v_and_b32_e32 v147, 0xffff0000, v129
	v_add_f32_e32 v0, v172, v0
	v_pk_mul_f32 v[174:175], v[146:147], v[146:147]
	v_add_f32_e32 v0, v173, v0
	v_add_f32_e32 v0, v174, v0
	v_add_f32_e32 v0, v175, v0
	ds_bpermute_b32 v66, v180, v0
	s_waitcnt lgkmcnt(0)
	v_add_f32_e32 v0, v0, v66
	ds_bpermute_b32 v66, v181, v0
	s_waitcnt lgkmcnt(0)
	v_add_f32_e32 v0, v0, v66
	ds_bpermute_b32 v66, v186, v0
	s_waitcnt lgkmcnt(0)
	v_add_f32_e32 v0, v0, v66
	v_fmamk_f32 v0, v0, 0x3c800000, v199
	v_cmp_gt_f32_e32 vcc, s21, v0
	v_mul_f32_e32 v66, 0x4f800000, v0
	s_nop 0
	v_cndmask_b32_e32 v0, v0, v66, vcc
	v_sqrt_f32_e32 v66, v0
	s_nop 0
	v_add_u32_e32 v82, -1, v66
	v_fma_f32 v170, -v82, v66, v0
	v_cmp_ge_f32_e64 s[52:53], 0, v170
	v_add_u32_e32 v170, 1, v66
	s_nop 0
	v_cndmask_b32_e64 v82, v66, v82, s[52:53]
	v_fma_f32 v66, -v170, v66, v0
	v_cmp_lt_f32_e64 s[52:53], 0, v66
	s_nop 1
	v_cndmask_b32_e64 v66, v82, v170, s[52:53]
	v_mul_f32_e32 v82, 0x37800000, v66
	v_cndmask_b32_e32 v66, v66, v82, vcc
	v_cmp_class_f32_e32 vcc, v0, v200
	s_nop 1
	v_cndmask_b32_e32 v0, v66, v0, vcc
	v_div_scale_f32 v66, s[0:1], v0, v0, 1.0
	v_rcp_f32_e32 v82, v66
	s_nop 0
	v_fma_f32 v170, -v66, v82, 1.0
	v_fmac_f32_e32 v82, v170, v82
	v_div_scale_f32 v170, vcc, 1.0, v0, 1.0
	v_mul_f32_e32 v171, v170, v82
	v_fma_f32 v172, -v66, v171, v170
	v_fmac_f32_e32 v171, v172, v82
	v_fma_f32 v66, -v66, v171, v170
	v_div_fmas_f32 v66, v66, v82, v171
	v_div_fixup_f32 v0, v66, v0, 1.0
	v_pk_mul_f32 v[170:171], v[0:1], v[168:169] op_sel_hi:[0,1]
	v_pk_mul_f32 v[172:173], v[0:1], v[166:167] op_sel_hi:[0,1]
	v_pk_mul_f32 v[174:175], v[0:1], v[148:149] op_sel_hi:[0,1]
	v_pk_mul_f32 v[176:177], v[0:1], v[146:147] op_sel_hi:[0,1]
	v_pk_mul_f32 v[170:171], v[14:15], v[170:171]
	v_pk_mul_f32 v[172:173], v[16:17], v[172:173]
	v_pk_mul_f32 v[174:175], v[10:11], v[174:175]
	v_pk_mul_f32 v[176:177], v[12:13], v[176:177]
	s_and_b64 vcc, exec, s[50:51]
	s_cbranch_vccnz .LBB0_405
	ds_bpermute_b32 v190, v181, v170
	ds_bpermute_b32 v191, v181, v171
	s_waitcnt vmcnt(2) lgkmcnt(0)
	v_pk_mul_f32 v[142:143], v[142:143], v[190:191]
	ds_bpermute_b32 v190, v181, v172
	ds_bpermute_b32 v191, v181, v173
	v_cndmask_b32_e64 v143, v143, -v143, s[44:45]
	v_cndmask_b32_e64 v142, v142, -v142, s[44:45]
	v_pk_fma_f32 v[170:171], v[130:131], v[170:171], v[142:143]
	s_waitcnt lgkmcnt(0)
	v_pk_mul_f32 v[144:145], v[144:145], v[190:191]
	ds_bpermute_b32 v190, v181, v174
	ds_bpermute_b32 v191, v181, v175
	v_cndmask_b32_e64 v145, v145, -v145, s[44:45]
	v_cndmask_b32_e64 v144, v144, -v144, s[44:45]
	v_pk_fma_f32 v[172:173], v[132:133], v[172:173], v[144:145]
	s_waitcnt vmcnt(1) lgkmcnt(0)
	v_pk_mul_f32 v[138:139], v[138:139], v[190:191]
	ds_bpermute_b32 v190, v181, v176
	ds_bpermute_b32 v191, v181, v177
	v_cndmask_b32_e64 v139, v139, -v139, s[44:45]
	v_cndmask_b32_e64 v138, v138, -v138, s[44:45]
	v_pk_fma_f32 v[174:175], v[134:135], v[174:175], v[138:139]
	s_waitcnt lgkmcnt(0)
	v_pk_mul_f32 v[140:141], v[140:141], v[190:191]
	s_nop 0
	v_cndmask_b32_e64 v140, v140, -v140, s[44:45]
	v_cndmask_b32_e64 v141, v141, -v141, s[44:45]
	v_pk_fma_f32 v[176:177], v[136:137], v[176:177], v[140:141]
	s_and_saveexec_b64 s[0:1], s[46:47]
	s_xor_b64 s[0:1], exec, s[0:1]
	s_cbranch_execnz .LBB0_406

.LBB0_392:
	s_ashr_i32 s11, s26, 31
	s_add_u32 s10, s24, s26
	s_addc_u32 s11, s25, s11
	s_lshl_b64 s[10:11], s[10:11], 8
	v_cvt_pk_bf16_f32 v126, v170, v171
	v_cvt_pk_bf16_f32 v127, v172, v173
	v_cvt_pk_bf16_f32 v128, v174, v175
	v_cvt_pk_bf16_f32 v129, v176, v177
	s_waitcnt vmcnt(3)
	v_lshl_add_u64 v[130:131], v[158:159], 0, s[10:11]
	global_store_dwordx4 v[130:131], v[126:129], off sc1
.LBB0_393:
	s_or_b64 exec, exec, s[0:1]
	s_waitcnt vmcnt(5)
	v_lshlrev_b32_e32 v128, 16, v122
	v_and_b32_e32 v129, 0xffff0000, v122
	v_lshlrev_b32_e32 v122, 16, v123
	v_and_b32_e32 v123, 0xffff0000, v123
	s_waitcnt vmcnt(3)
	v_pk_mul_f32 v[130:131], v[128:129], v[128:129]
	v_pk_mul_f32 v[132:133], v[122:123], v[122:123]
	v_add_f32_e32 v0, v130, v131
	v_lshlrev_b32_e32 v126, 16, v124
	v_and_b32_e32 v127, 0xffff0000, v124
	v_add_f32_e32 v0, v132, v0
	v_pk_mul_f32 v[134:135], v[126:127], v[126:127]
	v_add_f32_e32 v0, v133, v0
	v_lshlrev_b32_e32 v124, 16, v125
	v_and_b32_e32 v125, 0xffff0000, v125
	v_add_f32_e32 v0, v134, v0
	v_pk_mul_f32 v[136:137], v[124:125], v[124:125]
	v_add_f32_e32 v0, v135, v0
	v_add_f32_e32 v0, v136, v0
	v_add_f32_e32 v0, v137, v0
	s_and_saveexec_b64 s[0:1], s[40:41]
	s_xor_b64 s[0:1], exec, s[0:1]
	s_cbranch_execz .LBB0_395
	ds_bpermute_b32 v66, v180, v0
	s_waitcnt lgkmcnt(0)
	v_add_f32_e32 v0, v0, v66
	ds_bpermute_b32 v66, v181, v0
	s_waitcnt lgkmcnt(0)
	v_add_f32_e32 v0, v0, v66
	ds_bpermute_b32 v66, v186, v0
	s_waitcnt lgkmcnt(0)
	v_add_f32_e32 v0, v0, v66
	v_fmamk_f32 v0, v0, 0x3c800000, v199
	v_mul_f32_e32 v66, 0x4f800000, v0
	v_cmp_gt_f32_e32 vcc, s21, v0
	s_nop 1
	v_cndmask_b32_e32 v0, v0, v66, vcc
	v_sqrt_f32_e32 v66, v0
	s_nop 0
	v_add_u32_e32 v82, -1, v66
	v_add_u32_e32 v130, 1, v66
	v_fma_f32 v131, -v82, v66, v0
	v_fma_f32 v132, -v130, v66, v0
	v_cmp_ge_f32_e64 s[50:51], 0, v131
	s_nop 1
	v_cndmask_b32_e64 v66, v66, v82, s[50:51]
	v_cmp_lt_f32_e64 s[50:51], 0, v132
	s_nop 1
	v_cndmask_b32_e64 v66, v66, v130, s[50:51]
	v_mul_f32_e32 v82, 0x37800000, v66
	v_cndmask_b32_e32 v66, v66, v82, vcc
	v_cmp_class_f32_e32 vcc, v0, v200
	s_nop 1
	v_cndmask_b32_e32 v0, v66, v0, vcc
	v_div_scale_f32 v66, s[10:11], v0, v0, 1.0
	v_rcp_f32_e32 v82, v66
	v_div_scale_f32 v130, vcc, 1.0, v0, 1.0
	s_ashr_i32 s11, s26, 31
	v_fma_f32 v131, -v66, v82, 1.0
	v_fmac_f32_e32 v82, v131, v82
	v_mul_f32_e32 v131, v130, v82
	v_fma_f32 v132, -v66, v131, v130
	v_fmac_f32_e32 v131, v132, v82
	v_fma_f32 v66, -v66, v131, v130
	v_div_fmas_f32 v66, v66, v82, v131
	v_div_fixup_f32 v0, v66, v0, 1.0
	s_add_u32 s10, s24, s26
	v_pk_mul_f32 v[128:129], v[0:1], v[128:129] op_sel_hi:[0,1]
	v_pk_mul_f32 v[122:123], v[0:1], v[122:123] op_sel_hi:[0,1]
	v_pk_mul_f32 v[126:127], v[0:1], v[126:127] op_sel_hi:[0,1]
	v_pk_mul_f32 v[124:125], v[0:1], v[124:125] op_sel_hi:[0,1]
	s_addc_u32 s11, s25, s11
	v_pk_mul_f32 v[128:129], v[30:31], v[128:129]
	v_pk_mul_f32 v[130:131], v[32:33], v[122:123]
	v_pk_mul_f32 v[126:127], v[26:27], v[126:127]
	v_pk_mul_f32 v[132:133], v[28:29], v[124:125]
	s_lshl_b64 s[10:11], s[10:11], 9
	v_cvt_pk_bf16_f32 v122, v128, v129
	v_cvt_pk_bf16_f32 v123, v130, v131
	v_cvt_pk_bf16_f32 v124, v126, v127
	v_cvt_pk_bf16_f32 v125, v132, v133
	v_lshl_add_u64 v[126:127], v[160:161], 0, s[10:11]
	global_store_dwordx4 v[126:127], v[122:125], off offset:-512 sc1
.LBB0_395:
	s_andn2_saveexec_b64 s[0:1], s[0:1]
	s_cbranch_execz .LBB0_397
	ds_bpermute_b32 v66, v180, v0
	s_lshl_b64 s[8:9], s[8:9], 9
	s_waitcnt lgkmcnt(0)
	v_add_f32_e32 v0, v0, v66
	ds_bpermute_b32 v66, v181, v0
	s_waitcnt lgkmcnt(0)
	v_add_f32_e32 v0, v0, v66
	ds_bpermute_b32 v66, v186, v0
	s_waitcnt lgkmcnt(0)
	v_add_f32_e32 v0, v0, v66
	v_fmamk_f32 v0, v0, 0x3c800000, v199
	v_mul_f32_e32 v66, 0x4f800000, v0
	v_cmp_gt_f32_e32 vcc, s21, v0
	s_nop 1
	v_cndmask_b32_e32 v0, v0, v66, vcc
	v_sqrt_f32_e32 v66, v0
	s_nop 0
	v_add_u32_e32 v82, -1, v66
	v_add_u32_e32 v130, 1, v66
	v_fma_f32 v131, -v82, v66, v0
	v_fma_f32 v132, -v130, v66, v0
	v_cmp_ge_f32_e64 s[50:51], 0, v131
	s_nop 1
	v_cndmask_b32_e64 v66, v66, v82, s[50:51]
	v_cmp_lt_f32_e64 s[50:51], 0, v132
	s_nop 1
	v_cndmask_b32_e64 v66, v66, v130, s[50:51]
	v_mul_f32_e32 v82, 0x37800000, v66
	v_cndmask_b32_e32 v66, v66, v82, vcc
	v_cmp_class_f32_e32 vcc, v0, v200
	s_nop 1
	v_cndmask_b32_e32 v0, v66, v0, vcc
	v_div_scale_f32 v66, s[10:11], v0, v0, 1.0
	v_rcp_f32_e32 v82, v66
	v_div_scale_f32 v130, vcc, 1.0, v0, 1.0
	v_fma_f32 v131, -v66, v82, 1.0
	v_fmac_f32_e32 v82, v131, v82
	v_mul_f32_e32 v131, v130, v82
	v_fma_f32 v132, -v66, v131, v130
	v_fmac_f32_e32 v131, v132, v82
	v_fma_f32 v66, -v66, v131, v130
	v_div_fmas_f32 v66, v66, v82, v131
	v_div_fixup_f32 v0, v66, v0, 1.0
	v_pk_mul_f32 v[128:129], v[0:1], v[128:129] op_sel_hi:[0,1]
	v_pk_mul_f32 v[122:123], v[0:1], v[122:123] op_sel_hi:[0,1]
	v_pk_mul_f32 v[126:127], v[0:1], v[126:127] op_sel_hi:[0,1]
	v_pk_mul_f32 v[124:125], v[0:1], v[124:125] op_sel_hi:[0,1]
	v_pk_mul_f32 v[128:129], v[22:23], v[128:129]
	v_pk_mul_f32 v[122:123], v[24:25], v[122:123]
	v_pk_mul_f32 v[126:127], v[18:19], v[126:127]
	v_pk_mul_f32 v[124:125], v[20:21], v[124:125]
	v_pk_mul_f32 v[128:129], v[128:129], s[20:21] op_sel_hi:[1,0]
	v_pk_mul_f32 v[130:131], v[122:123], s[20:21] op_sel_hi:[1,0]
	v_pk_mul_f32 v[126:127], v[126:127], s[20:21] op_sel_hi:[1,0]
	v_pk_mul_f32 v[132:133], v[124:125], s[20:21] op_sel_hi:[1,0]
	v_cvt_pk_bf16_f32 v122, v128, v129
	v_cvt_pk_bf16_f32 v123, v130, v131
	v_cvt_pk_bf16_f32 v124, v126, v127
	v_cvt_pk_bf16_f32 v125, v132, v133
	v_lshl_add_u64 v[126:127], v[162:163], 0, s[8:9]
	global_store_dwordx4 v[126:127], v[122:125], off sc1

.LBB0_406:
	s_and_saveexec_b64 s[10:11], s[48:49]
	s_cbranch_execz .LBB0_408
	s_ashr_i32 s27, s26, 31
	s_add_u32 s28, s24, s26
	s_addc_u32 s29, s25, s27
	s_lshl_b64 s[28:29], s[28:29], 8
	s_waitcnt vmcnt(3)
	v_lshl_add_u64 v[130:131], v[156:157], 0, s[28:29]
	global_store_dwordx4 v[130:131], v[126:129], off offset:-256 sc1

.LBB0_507:
	s_or_b64 exec, exec, s[0:1]
	s_waitcnt lgkmcnt(0)
	ds_read_b128 v[34:37], v50 offset:49280
	ds_read_b128 v[38:41], v50 offset:49312
	s_lshl_b64 s[0:1], s[46:47], 11
	v_readlane_b32 s2, v250, 15
	v_readlane_b32 s3, v250, 16
	s_waitcnt lgkmcnt(1)
	v_rcp_f32_e32 v0, v34
	v_rcp_f32_e32 v42, v35
	s_add_u32 s0, s2, s0
	s_addc_u32 s1, s3, s1
	s_lshl_b32 s2, s10, 12
	v_rcp_f32_e32 v43, v36
	v_rcp_f32_e32 v44, v37
	s_waitcnt lgkmcnt(0)
	v_rcp_f32_e32 v45, v38
	ds_read_b128 v[34:37], v50 offset:49344
	v_rcp_f32_e32 v46, v39
	v_rcp_f32_e32 v47, v40
	v_rcp_f32_e32 v48, v41
	ds_read_b128 v[38:41], v50 offset:49376
	s_add_i32 s2, s2, 0
	v_lshlrev_b32_e32 v49, 9, v214
	v_lshlrev_b32_e32 v50, 1, v197
	v_mul_f32_e32 v2, v2, v0
	v_mul_f32_e32 v0, v18, v0
	v_add3_u32 v49, s2, v49, v50
	v_cvt_pk_bf16_f32 v0, v0, s0
	ds_write_b16 v49, v0 offset:51264
	v_mul_f32_e32 v0, v3, v42
	v_cvt_pk_bf16_f32 v0, v0, s0
	ds_write_b16 v49, v0 offset:51328
	v_mul_f32_e32 v0, v19, v42
	v_cvt_pk_bf16_f32 v0, v0, s0
	ds_write_b16 v49, v0 offset:51392
	v_mul_f32_e32 v0, v4, v43
	v_cvt_pk_bf16_f32 v0, v0, s0
	ds_write_b16 v49, v0 offset:51456
	v_mul_f32_e32 v0, v20, v43
	v_cvt_pk_bf16_f32 v0, v0, s0
	ds_write_b16 v49, v0 offset:51520
	v_mul_f32_e32 v0, v5, v44
	v_cvt_pk_bf16_f32 v0, v0, s0
	ds_write_b16 v49, v0 offset:51584
	v_mul_f32_e32 v0, v21, v44
	v_cvt_pk_bf16_f32 v0, v0, s0
	ds_write_b16 v49, v0 offset:51648
	v_mul_f32_e32 v0, v6, v45
	v_cvt_pk_bf16_f32 v0, v0, s0
	ds_write_b16 v49, v0 offset:52224
	v_mul_f32_e32 v0, v22, v45
	v_cvt_pk_bf16_f32 v0, v0, s0
	ds_write_b16 v49, v0 offset:52288
	v_mul_f32_e32 v0, v7, v46
	v_cvt_pk_bf16_f32 v0, v0, s0
	ds_write_b16 v49, v0 offset:52352
	v_mul_f32_e32 v0, v23, v46
	v_cvt_pk_bf16_f32 v0, v0, s0
	ds_write_b16 v49, v0 offset:52416
	v_mul_f32_e32 v0, v8, v47
	v_cvt_pk_bf16_f32 v0, v0, s0
	ds_write_b16 v49, v0 offset:52480
	v_mul_f32_e32 v0, v24, v47
	v_cvt_pk_bf16_f32 v0, v0, s0
	s_waitcnt lgkmcnt(13)
	v_rcp_f32_e32 v34, v34
	ds_write_b16 v49, v0 offset:52544
	v_mul_f32_e32 v0, v9, v48
	v_cvt_pk_bf16_f32 v0, v0, s0
	ds_write_b16 v49, v0 offset:52608
	v_mul_f32_e32 v0, v25, v48
	v_cvt_pk_bf16_f32 v0, v0, s0
	v_rcp_f32_e32 v35, v35
	ds_write_b16 v49, v0 offset:52672
	v_mul_f32_e32 v0, v10, v34
	v_cvt_pk_bf16_f32 v0, v0, s0
	ds_write_b16 v49, v0 offset:53248
	v_mul_f32_e32 v0, v26, v34
	v_cvt_pk_bf16_f32 v0, v0, s0
	v_rcp_f32_e32 v36, v36
	ds_write_b16 v49, v0 offset:53312
	v_mul_f32_e32 v0, v11, v35
	v_cvt_pk_bf16_f32 v0, v0, s0
	ds_write_b16 v49, v0 offset:53376
	v_mul_f32_e32 v0, v27, v35
	v_cvt_pk_bf16_f32 v0, v0, s0
	v_rcp_f32_e32 v37, v37
	ds_write_b16 v49, v0 offset:53440
	v_mul_f32_e32 v0, v12, v36
	v_cvt_pk_bf16_f32 v0, v0, s0
	ds_write_b16 v49, v0 offset:53504
	v_mul_f32_e32 v0, v28, v36
	v_cvt_pk_bf16_f32 v0, v0, s0
	s_waitcnt lgkmcnt(14)
	v_rcp_f32_e32 v38, v38
	ds_write_b16 v49, v0 offset:53568
	v_mul_f32_e32 v0, v13, v37
	v_cvt_pk_bf16_f32 v0, v0, s0
	ds_write_b16 v49, v0 offset:53632
	v_mul_f32_e32 v0, v29, v37
	v_cvt_pk_bf16_f32 v0, v0, s0
	v_rcp_f32_e32 v39, v39
	ds_write_b16 v49, v0 offset:53696
	v_mul_f32_e32 v0, v14, v38
	v_cvt_pk_bf16_f32 v0, v0, s0
	ds_write_b16 v49, v0 offset:54272
	v_mul_f32_e32 v0, v30, v38
	v_cvt_pk_bf16_f32 v0, v0, s0
	v_rcp_f32_e32 v40, v40
	ds_write_b16 v49, v0 offset:54336
	v_mul_f32_e32 v0, v15, v39
	v_cvt_pk_bf16_f32 v0, v0, s0
	ds_write_b16 v49, v0 offset:54400
	v_mul_f32_e32 v0, v31, v39
	v_cvt_pk_bf16_f32 v0, v0, s0
	v_rcp_f32_e32 v41, v41
	ds_write_b16 v49, v0 offset:54464
	v_mul_f32_e32 v0, v16, v40
	v_cvt_pk_bf16_f32 v0, v0, s0
	ds_write_b16 v49, v0 offset:54528
	v_mul_f32_e32 v0, v32, v40
	v_cvt_pk_bf16_f32 v0, v0, s0
	ds_write_b16 v49, v0 offset:54592
	v_mul_f32_e32 v0, v17, v41
	v_cvt_pk_bf16_f32 v0, v0, s0
	ds_write_b16 v49, v0 offset:54656
	v_mul_f32_e32 v0, v33, v41
	v_cvt_pk_bf16_f32 v0, v0, s0
	ds_write_b16 v49, v0 offset:54720
	v_lshlrev_b32_e32 v0, 1, v196
	v_cvt_pk_bf16_f32 v2, v2, s0
	s_add_u32 s0, s0, s44
	v_and_b32_e32 v0, 0x70, v0
	ds_write_b16 v49, v2 offset:51200
	s_addc_u32 s1, s1, s45
	v_lshrrev_b32_e32 v14, 3, v187
	v_add_u32_e32 v15, s2, v0
	s_waitcnt lgkmcnt(0)
	v_lshl_add_u64 v[10:11], s[0:1], 0, v[0:1]
	v_lshl_add_u32 v0, v14, 7, v15
	v_or_b32_e32 v16, 8, v14
	ds_read_b128 v[2:5], v0 offset:51200
	v_lshl_add_u32 v6, v16, 7, v15
	ds_read_b128 v[6:9], v6 offset:51200
	v_lshlrev_b32_e32 v0, 11, v14
	v_lshl_add_u64 v[12:13], v[10:11], 0, v[0:1]
	v_lshlrev_b32_e32 v0, 11, v16
	s_waitcnt lgkmcnt(1)
	global_store_dwordx4 v[12:13], v[2:5], off sc1
	s_mov_b32 s2, 64
	s_mov_b64 s[0:1], 0
	v_lshl_add_u64 v[2:3], v[10:11], 0, v[0:1]
	v_or_b32_e32 v0, 16, v14
	s_waitcnt lgkmcnt(0)
	global_store_dwordx4 v[2:3], v[6:9], off sc1
	v_lshl_add_u32 v2, v0, 7, v15
	v_or_b32_e32 v14, 24, v14
	ds_read_b128 v[2:5], v2 offset:51200
	v_lshl_add_u32 v6, v14, 7, v15
	ds_read_b128 v[6:9], v6 offset:51200
	v_lshlrev_b32_e32 v0, 11, v0
	v_lshl_add_u64 v[12:13], v[10:11], 0, v[0:1]
	v_lshlrev_b32_e32 v0, 11, v14
	s_waitcnt lgkmcnt(1)
	global_store_dwordx4 v[12:13], v[2:5], off sc1
	s_and_b64 vcc, exec, s[42:43]
	s_nop 0
	v_lshl_add_u64 v[2:3], v[10:11], 0, v[0:1]
	s_waitcnt lgkmcnt(0)
	global_store_dwordx4 v[2:3], v[6:9], off sc1
	s_waitcnt lgkmcnt(0)
	s_barrier
	s_cbranch_vccnz .LBB0_625

.LBB0_566:
	s_or_b64 exec, exec, s[0:1]
	s_waitcnt lgkmcnt(0)
	ds_read_b128 v[34:37], v50 offset:49280
	ds_read_b128 v[38:41], v50 offset:49312
	s_lshl_b64 s[0:1], s[42:43], 11
	v_readlane_b32 s2, v250, 15
	v_readlane_b32 s3, v250, 16
	s_waitcnt lgkmcnt(1)
	v_rcp_f32_e32 v0, v34
	v_rcp_f32_e32 v42, v35
	s_add_u32 s0, s2, s0
	s_addc_u32 s1, s3, s1
	s_lshl_b32 s2, s14, 12
	v_rcp_f32_e32 v43, v36
	v_rcp_f32_e32 v44, v37
	s_waitcnt lgkmcnt(0)
	v_rcp_f32_e32 v45, v38
	ds_read_b128 v[34:37], v50 offset:49344
	v_rcp_f32_e32 v46, v39
	v_rcp_f32_e32 v47, v40
	v_rcp_f32_e32 v48, v41
	ds_read_b128 v[38:41], v50 offset:49376
	s_add_i32 s2, s2, 0
	v_lshlrev_b32_e32 v49, 9, v214
	v_lshlrev_b32_e32 v50, 1, v197
	v_mul_f32_e32 v2, v2, v0
	v_mul_f32_e32 v0, v18, v0
	v_add3_u32 v49, s2, v49, v50
	v_cvt_pk_bf16_f32 v0, v0, s0
	ds_write_b16 v49, v0 offset:51264
	v_mul_f32_e32 v0, v3, v42
	v_cvt_pk_bf16_f32 v0, v0, s0
	ds_write_b16 v49, v0 offset:51328
	v_mul_f32_e32 v0, v19, v42
	v_cvt_pk_bf16_f32 v0, v0, s0
	ds_write_b16 v49, v0 offset:51392
	v_mul_f32_e32 v0, v4, v43
	v_cvt_pk_bf16_f32 v0, v0, s0
	ds_write_b16 v49, v0 offset:51456
	v_mul_f32_e32 v0, v20, v43
	v_cvt_pk_bf16_f32 v0, v0, s0
	ds_write_b16 v49, v0 offset:51520
	v_mul_f32_e32 v0, v5, v44
	v_cvt_pk_bf16_f32 v0, v0, s0
	ds_write_b16 v49, v0 offset:51584
	v_mul_f32_e32 v0, v21, v44
	v_cvt_pk_bf16_f32 v0, v0, s0
	ds_write_b16 v49, v0 offset:51648
	v_mul_f32_e32 v0, v6, v45
	v_cvt_pk_bf16_f32 v0, v0, s0
	ds_write_b16 v49, v0 offset:52224
	v_mul_f32_e32 v0, v22, v45
	v_cvt_pk_bf16_f32 v0, v0, s0
	ds_write_b16 v49, v0 offset:52288
	v_mul_f32_e32 v0, v7, v46
	v_cvt_pk_bf16_f32 v0, v0, s0
	ds_write_b16 v49, v0 offset:52352
	v_mul_f32_e32 v0, v23, v46
	v_cvt_pk_bf16_f32 v0, v0, s0
	ds_write_b16 v49, v0 offset:52416
	v_mul_f32_e32 v0, v8, v47
	v_cvt_pk_bf16_f32 v0, v0, s0
	ds_write_b16 v49, v0 offset:52480
	v_mul_f32_e32 v0, v24, v47
	v_cvt_pk_bf16_f32 v0, v0, s0
	s_waitcnt lgkmcnt(13)
	v_rcp_f32_e32 v34, v34
	ds_write_b16 v49, v0 offset:52544
	v_mul_f32_e32 v0, v9, v48
	v_cvt_pk_bf16_f32 v0, v0, s0
	ds_write_b16 v49, v0 offset:52608
	v_mul_f32_e32 v0, v25, v48
	v_cvt_pk_bf16_f32 v0, v0, s0
	v_rcp_f32_e32 v35, v35
	ds_write_b16 v49, v0 offset:52672
	v_mul_f32_e32 v0, v10, v34
	v_cvt_pk_bf16_f32 v0, v0, s0
	ds_write_b16 v49, v0 offset:53248
	v_mul_f32_e32 v0, v26, v34
	v_cvt_pk_bf16_f32 v0, v0, s0
	v_rcp_f32_e32 v36, v36
	ds_write_b16 v49, v0 offset:53312
	v_mul_f32_e32 v0, v11, v35
	v_cvt_pk_bf16_f32 v0, v0, s0
	ds_write_b16 v49, v0 offset:53376
	v_mul_f32_e32 v0, v27, v35
	v_cvt_pk_bf16_f32 v0, v0, s0
	v_rcp_f32_e32 v37, v37
	ds_write_b16 v49, v0 offset:53440
	v_mul_f32_e32 v0, v12, v36
	v_cvt_pk_bf16_f32 v0, v0, s0
	ds_write_b16 v49, v0 offset:53504
	v_mul_f32_e32 v0, v28, v36
	v_cvt_pk_bf16_f32 v0, v0, s0
	s_waitcnt lgkmcnt(14)
	v_rcp_f32_e32 v38, v38
	ds_write_b16 v49, v0 offset:53568
	v_mul_f32_e32 v0, v13, v37
	v_cvt_pk_bf16_f32 v0, v0, s0
	ds_write_b16 v49, v0 offset:53632
	v_mul_f32_e32 v0, v29, v37
	v_cvt_pk_bf16_f32 v0, v0, s0
	v_rcp_f32_e32 v39, v39
	ds_write_b16 v49, v0 offset:53696
	v_mul_f32_e32 v0, v14, v38
	v_cvt_pk_bf16_f32 v0, v0, s0
	ds_write_b16 v49, v0 offset:54272
	v_mul_f32_e32 v0, v30, v38
	v_cvt_pk_bf16_f32 v0, v0, s0
	v_rcp_f32_e32 v40, v40
	ds_write_b16 v49, v0 offset:54336
	v_mul_f32_e32 v0, v15, v39
	v_cvt_pk_bf16_f32 v0, v0, s0
	ds_write_b16 v49, v0 offset:54400
	v_mul_f32_e32 v0, v31, v39
	v_cvt_pk_bf16_f32 v0, v0, s0
	v_rcp_f32_e32 v41, v41
	ds_write_b16 v49, v0 offset:54464
	v_mul_f32_e32 v0, v16, v40
	v_cvt_pk_bf16_f32 v0, v0, s0
	ds_write_b16 v49, v0 offset:54528
	v_mul_f32_e32 v0, v32, v40
	v_cvt_pk_bf16_f32 v0, v0, s0
	ds_write_b16 v49, v0 offset:54592
	v_mul_f32_e32 v0, v17, v41
	v_cvt_pk_bf16_f32 v0, v0, s0
	ds_write_b16 v49, v0 offset:54656
	v_mul_f32_e32 v0, v33, v41
	v_cvt_pk_bf16_f32 v0, v0, s0
	ds_write_b16 v49, v0 offset:54720
	s_lshl_b32 s3, s11, 1
	v_lshlrev_b32_e32 v0, 1, v196
	v_cvt_pk_bf16_f32 v2, v2, s0
	s_add_u32 s0, s0, s3
	v_and_b32_e32 v0, 0x70, v0
	ds_write_b16 v49, v2 offset:51200
	s_addc_u32 s1, s1, 0
	v_lshrrev_b32_e32 v14, 3, v187
	v_add_u32_e32 v15, s2, v0
	s_waitcnt lgkmcnt(0)
	v_lshl_add_u64 v[10:11], s[0:1], 0, v[0:1]
	v_lshl_add_u32 v0, v14, 7, v15
	v_or_b32_e32 v16, 8, v14
	ds_read_b128 v[2:5], v0 offset:51200
	v_lshl_add_u32 v6, v16, 7, v15
	ds_read_b128 v[6:9], v6 offset:51200
	v_lshlrev_b32_e32 v0, 11, v14
	v_lshl_add_u64 v[12:13], v[10:11], 0, v[0:1]
	v_lshlrev_b32_e32 v0, 11, v16
	s_waitcnt lgkmcnt(1)
	global_store_dwordx4 v[12:13], v[2:5], off sc1
	s_add_i32 s10, s10, s94
	s_cmpk_lt_i32 s10, 0x200
	v_lshl_add_u64 v[2:3], v[10:11], 0, v[0:1]
	v_or_b32_e32 v0, 16, v14
	s_waitcnt lgkmcnt(0)
	global_store_dwordx4 v[2:3], v[6:9], off sc1
	v_lshl_add_u32 v2, v0, 7, v15
	v_or_b32_e32 v14, 24, v14
	ds_read_b128 v[2:5], v2 offset:51200
	v_lshl_add_u32 v6, v14, 7, v15
	ds_read_b128 v[6:9], v6 offset:51200
	v_lshlrev_b32_e32 v0, 11, v0
	v_lshl_add_u64 v[12:13], v[10:11], 0, v[0:1]
	v_lshlrev_b32_e32 v0, 11, v14
	s_waitcnt lgkmcnt(1)
	global_store_dwordx4 v[12:13], v[2:5], off sc1
	s_nop 1
	v_lshl_add_u64 v[2:3], v[10:11], 0, v[0:1]
	s_waitcnt lgkmcnt(0)
	global_store_dwordx4 v[2:3], v[6:9], off sc1
	s_waitcnt lgkmcnt(0)
	s_barrier
	s_cbranch_scc0 .LBB0_469

.LBB0_629:
	s_or_b64 exec, exec, s[0:1]
	s_waitcnt lgkmcnt(0)
	ds_read_b128 v[2:5], v214 offset:49280
	ds_read_b128 v[6:9], v214 offset:49312
	s_lshl_b64 s[0:1], s[42:43], 11
	v_readlane_b32 s6, v250, 15
	v_readlane_b32 s7, v250, 16
	s_waitcnt lgkmcnt(1)
	v_rcp_f32_e32 v0, v2
	v_rcp_f32_e32 v10, v3
	s_add_u32 s0, s6, s0
	s_addc_u32 s1, s7, s1
	s_lshl_b32 s3, s5, 12
	s_add_i32 s3, s3, 0
	v_lshlrev_b32_e32 v17, 9, v192
	v_lshlrev_b32_e32 v50, 1, v191
	v_mul_f32_e32 v18, v18, v0
	v_mul_f32_e32 v0, v34, v0
	v_add3_u32 v17, s3, v17, v50
	v_cvt_pk_bf16_f32 v0, v0, s0
	v_rcp_f32_e32 v11, v4
	v_rcp_f32_e32 v12, v5
	s_waitcnt lgkmcnt(0)
	v_rcp_f32_e32 v13, v6
	ds_read_b128 v[2:5], v214 offset:49344
	v_rcp_f32_e32 v14, v7
	v_rcp_f32_e32 v15, v8
	v_rcp_f32_e32 v16, v9
	ds_read_b128 v[6:9], v214 offset:49376
	ds_write_b16 v17, v0 offset:51264
	v_mul_f32_e32 v0, v19, v10
	v_cvt_pk_bf16_f32 v0, v0, s0
	ds_write_b16 v17, v0 offset:51328
	v_mul_f32_e32 v0, v35, v10
	v_cvt_pk_bf16_f32 v0, v0, s0
	ds_write_b16 v17, v0 offset:51392
	v_mul_f32_e32 v0, v20, v11
	v_cvt_pk_bf16_f32 v0, v0, s0
	ds_write_b16 v17, v0 offset:51456
	v_mul_f32_e32 v0, v36, v11
	v_cvt_pk_bf16_f32 v0, v0, s0
	ds_write_b16 v17, v0 offset:51520
	v_mul_f32_e32 v0, v21, v12
	v_cvt_pk_bf16_f32 v0, v0, s0
	ds_write_b16 v17, v0 offset:51584
	v_mul_f32_e32 v0, v37, v12
	v_cvt_pk_bf16_f32 v0, v0, s0
	ds_write_b16 v17, v0 offset:51648
	v_mul_f32_e32 v0, v22, v13
	v_cvt_pk_bf16_f32 v0, v0, s0
	ds_write_b16 v17, v0 offset:52224
	v_mul_f32_e32 v0, v38, v13
	v_cvt_pk_bf16_f32 v0, v0, s0
	ds_write_b16 v17, v0 offset:52288
	v_mul_f32_e32 v0, v23, v14
	v_cvt_pk_bf16_f32 v0, v0, s0
	ds_write_b16 v17, v0 offset:52352
	v_mul_f32_e32 v0, v39, v14
	v_cvt_pk_bf16_f32 v0, v0, s0
	ds_write_b16 v17, v0 offset:52416
	v_mul_f32_e32 v0, v24, v15
	v_cvt_pk_bf16_f32 v0, v0, s0
	ds_write_b16 v17, v0 offset:52480
	v_mul_f32_e32 v0, v40, v15
	v_cvt_pk_bf16_f32 v0, v0, s0
	s_waitcnt lgkmcnt(13)
	v_rcp_f32_e32 v2, v2
	ds_write_b16 v17, v0 offset:52544
	v_mul_f32_e32 v0, v25, v16
	v_cvt_pk_bf16_f32 v0, v0, s0
	ds_write_b16 v17, v0 offset:52608
	v_mul_f32_e32 v0, v41, v16
	v_cvt_pk_bf16_f32 v0, v0, s0
	v_rcp_f32_e32 v3, v3
	ds_write_b16 v17, v0 offset:52672
	v_mul_f32_e32 v0, v26, v2
	v_cvt_pk_bf16_f32 v0, v0, s0
	ds_write_b16 v17, v0 offset:53248
	v_mul_f32_e32 v0, v42, v2
	v_cvt_pk_bf16_f32 v0, v0, s0
	v_rcp_f32_e32 v4, v4
	ds_write_b16 v17, v0 offset:53312
	v_mul_f32_e32 v0, v27, v3
	v_cvt_pk_bf16_f32 v0, v0, s0
	ds_write_b16 v17, v0 offset:53376
	v_mul_f32_e32 v0, v43, v3
	v_cvt_pk_bf16_f32 v0, v0, s0
	v_rcp_f32_e32 v5, v5
	ds_write_b16 v17, v0 offset:53440
	v_mul_f32_e32 v0, v28, v4
	v_cvt_pk_bf16_f32 v0, v0, s0
	ds_write_b16 v17, v0 offset:53504
	v_mul_f32_e32 v0, v44, v4
	v_cvt_pk_bf16_f32 v0, v0, s0
	s_waitcnt lgkmcnt(14)
	v_rcp_f32_e32 v6, v6
	ds_write_b16 v17, v0 offset:53568
	v_mul_f32_e32 v0, v29, v5
	v_cvt_pk_bf16_f32 v0, v0, s0
	ds_write_b16 v17, v0 offset:53632
	v_mul_f32_e32 v0, v45, v5
	v_cvt_pk_bf16_f32 v0, v0, s0
	v_rcp_f32_e32 v7, v7
	ds_write_b16 v17, v0 offset:53696
	v_mul_f32_e32 v0, v30, v6
	v_cvt_pk_bf16_f32 v0, v0, s0
	ds_write_b16 v17, v0 offset:54272
	v_mul_f32_e32 v0, v46, v6
	v_cvt_pk_bf16_f32 v0, v0, s0
	v_rcp_f32_e32 v8, v8
	ds_write_b16 v17, v0 offset:54336
	v_mul_f32_e32 v0, v31, v7
	v_cvt_pk_bf16_f32 v0, v0, s0
	ds_write_b16 v17, v0 offset:54400
	v_mul_f32_e32 v0, v47, v7
	v_cvt_pk_bf16_f32 v0, v0, s0
	v_rcp_f32_e32 v9, v9
	ds_write_b16 v17, v0 offset:54464
	v_mul_f32_e32 v0, v32, v8
	v_cvt_pk_bf16_f32 v0, v0, s0
	ds_write_b16 v17, v0 offset:54528
	v_mul_f32_e32 v0, v48, v8
	v_cvt_pk_bf16_f32 v0, v0, s0
	ds_write_b16 v17, v0 offset:54592
	v_mul_f32_e32 v0, v33, v9
	v_cvt_pk_bf16_f32 v0, v0, s0
	ds_write_b16 v17, v0 offset:54656
	v_mul_f32_e32 v0, v49, v9
	v_cvt_pk_bf16_f32 v0, v0, s0
	ds_write_b16 v17, v0 offset:54720
	s_lshl_b32 s2, s2, 1
	v_lshlrev_b32_e32 v0, 1, v190
	v_cvt_pk_bf16_f32 v18, v18, s0
	s_add_u32 s0, s0, s2
	v_and_b32_e32 v0, 0x70, v0
	ds_write_b16 v17, v18 offset:51200
	s_addc_u32 s1, s1, 0
	v_lshrrev_b32_e32 v14, 3, v187
	v_add_u32_e32 v15, s3, v0
	s_waitcnt lgkmcnt(0)
	v_lshl_add_u64 v[10:11], s[0:1], 0, v[0:1]
	v_lshl_add_u32 v0, v14, 7, v15
	v_or_b32_e32 v16, 8, v14
	ds_read_b128 v[2:5], v0 offset:51200
	v_lshl_add_u32 v6, v16, 7, v15
	ds_read_b128 v[6:9], v6 offset:51200
	v_lshlrev_b32_e32 v0, 11, v14
	v_lshl_add_u64 v[12:13], v[10:11], 0, v[0:1]
	v_lshlrev_b32_e32 v0, 11, v16
	s_waitcnt lgkmcnt(1)
	global_store_dwordx4 v[12:13], v[2:5], off sc1
	s_add_i32 s4, s4, s94
	s_cmp_lt_i32 s4, 16
	v_lshl_add_u64 v[2:3], v[10:11], 0, v[0:1]
	v_or_b32_e32 v0, 16, v14
	s_waitcnt lgkmcnt(0)
	global_store_dwordx4 v[2:3], v[6:9], off sc1
	v_lshl_add_u32 v2, v0, 7, v15
	v_or_b32_e32 v14, 24, v14
	ds_read_b128 v[2:5], v2 offset:51200
	v_lshl_add_u32 v6, v14, 7, v15
	ds_read_b128 v[6:9], v6 offset:51200
	v_lshlrev_b32_e32 v0, 11, v0
	v_lshl_add_u64 v[12:13], v[10:11], 0, v[0:1]
	v_lshlrev_b32_e32 v0, 11, v14
	s_waitcnt lgkmcnt(1)
	global_store_dwordx4 v[12:13], v[2:5], off sc1
	s_nop 1
	v_lshl_add_u64 v[2:3], v[10:11], 0, v[0:1]
	s_waitcnt lgkmcnt(0)
	global_store_dwordx4 v[2:3], v[6:9], off sc1
	s_waitcnt lgkmcnt(0)
	s_barrier
	s_cbranch_scc0 .LBB0_626

.LBB0_1045:
	s_ashr_i32 s3, s2, 31
	s_ashr_i32 s5, s4, 31
	s_lshl_b64 s[0:1], s[4:5], 20
	s_lshl_b64 s[2:3], s[2:3], 21
	v_readlane_b32 s4, v251, 39
	v_lshlrev_b32_e32 v0, 2, v132
	v_readlane_b32 s5, v251, 40
	s_add_u32 s0, s4, s0
	v_lshl_or_b32 v0, s37, 8, v0
	s_addc_u32 s1, s5, s1
	v_or_b32_e32 v130, s34, v0
	s_add_u32 s0, s0, s2
	s_addc_u32 s1, s1, s3
	v_ashrrev_i32_e32 v131, 31, v130
	v_readlane_b32 s2, v254, 39
	v_lshlrev_b64 v[148:149], 2, v[130:131]
	v_readlane_b32 s3, v254, 40
	s_barrier
	v_or_b32_e32 v146, s12, v146
	v_lshl_add_u64 v[130:131], s[2:3], 0, v[148:149]
	global_load_dwordx4 v[142:145], v[130:131], off
	global_load_dwordx4 v[138:141], v[130:131], off offset:64
	global_load_dwordx4 v[134:137], v[130:131], off offset:512
	s_nop 0
	global_load_dwordx4 v[130:133], v[130:131], off offset:576
	s_ashr_i32 s2, s12, 31
	v_mov_b32_e32 v147, s2
	v_lshlrev_b64 v[146:147], 12, v[146:147]
	v_lshl_add_u64 v[146:147], s[0:1], 0, v[146:147]
	s_brev_b32 s0, 63
	v_lshl_add_u64 v[146:147], v[146:147], 0, v[148:149]
	s_mov_b32 s1, -1
	v_lshl_add_u64 v[148:149], v[146:147], 0, s[0:1]
	s_brev_b32 s0, 63
	v_add_co_u32_e32 v150, vcc, s0, v146
	s_mov_b32 s0, 0xfc010000
	s_nop 0
	v_addc_co_u32_e32 v151, vcc, -1, v147, vcc
	v_readlane_b32 s30, v254, 4
	v_readlane_b32 s34, v254, 6
	v_readlane_b32 s31, v254, 5
	v_readlane_b32 s35, v254, 7
	s_waitcnt vmcnt(0)
	v_pk_mul_f32 v[64:65], v[64:65], v[144:145]
	v_pk_mul_f32 v[62:63], v[62:63], v[142:143]
	v_pk_mul_f32 v[116:117], v[116:117], v[136:137]
	v_pk_mul_f32 v[114:115], v[114:115], v[134:135]
	global_store_dwordx4 v[148:149], v[114:117], off offset:512 sc1
	v_pk_mul_f32 v[112:113], v[112:113], v[132:133]
	v_pk_mul_f32 v[110:111], v[110:111], v[130:131]
	v_add_co_u32_e32 v114, vcc, s0, v146
	global_store_dwordx4 v[148:149], v[110:113], off offset:576 sc1
	s_nop 0
	v_addc_co_u32_e32 v115, vcc, -1, v147, vcc
	v_pk_mul_f32 v[112:113], v[120:121], v[144:145]
	v_pk_mul_f32 v[110:111], v[118:119], v[142:143]
	s_mov_b32 s0, 0xfc011000
	global_store_dwordx4 v[114:115], v[110:113], off sc1
	v_pk_mul_f32 v[100:101], v[100:101], v[136:137]
	v_pk_mul_f32 v[98:99], v[98:99], v[134:135]
	v_add_co_u32_e32 v110, vcc, s0, v146
	s_mov_b32 s0, 0xfc020000
	s_nop 0
	v_addc_co_u32_e32 v111, vcc, -1, v147, vcc
	global_store_dwordx4 v[110:111], v[98:101], off offset:-3584 sc1
	v_pk_mul_f32 v[96:97], v[96:97], v[132:133]
	v_pk_mul_f32 v[94:95], v[94:95], v[130:131]
	v_add_co_u32_e32 v98, vcc, s0, v146
	global_store_dwordx4 v[110:111], v[94:97], off offset:-3520 sc1
	s_nop 0
	v_addc_co_u32_e32 v99, vcc, -1, v147, vcc
	v_pk_mul_f32 v[96:97], v[104:105], v[144:145]
	v_pk_mul_f32 v[94:95], v[102:103], v[142:143]
	s_mov_b32 s0, 0xfc021000
	global_store_dwordx4 v[98:99], v[94:97], off sc1
	v_pk_mul_f32 v[84:85], v[84:85], v[136:137]
	v_pk_mul_f32 v[82:83], v[82:83], v[134:135]
	v_add_co_u32_e32 v94, vcc, s0, v146
	s_mov_b32 s0, 0xfc030000
	s_nop 0
	v_addc_co_u32_e32 v95, vcc, -1, v147, vcc
	global_store_dwordx4 v[94:95], v[82:85], off offset:-3584 sc1
	v_pk_mul_f32 v[80:81], v[80:81], v[132:133]
	v_pk_mul_f32 v[78:79], v[78:79], v[130:131]
	v_add_co_u32_e32 v82, vcc, s0, v146
	global_store_dwordx4 v[94:95], v[78:81], off offset:-3520 sc1
	s_nop 0
	v_addc_co_u32_e32 v83, vcc, -1, v147, vcc
	v_pk_mul_f32 v[80:81], v[88:89], v[144:145]
	v_pk_mul_f32 v[78:79], v[86:87], v[142:143]
	s_mov_b32 s0, 0xfc031000
	global_store_dwordx4 v[82:83], v[78:81], off sc1
	v_pk_mul_f32 v[68:69], v[68:69], v[132:133]
	v_pk_mul_f32 v[66:67], v[66:67], v[130:131]
	v_add_co_u32_e32 v78, vcc, s0, v146
	s_mov_b32 s0, 0xfc080000
	s_nop 0
	v_addc_co_u32_e32 v79, vcc, -1, v147, vcc
	global_store_dwordx4 v[78:79], v[66:69], off offset:-3520 sc1
	v_pk_mul_f32 v[48:49], v[48:49], v[136:137]
	v_pk_mul_f32 v[46:47], v[46:47], v[134:135]
	v_add_co_u32_e32 v66, vcc, s0, v146
	s_mov_b32 s0, 0xfc081000
	s_nop 0
	v_addc_co_u32_e32 v67, vcc, -1, v147, vcc
	global_store_dwordx4 v[66:67], v[62:65], off sc1
	v_pk_mul_f32 v[44:45], v[44:45], v[132:133]
	v_pk_mul_f32 v[42:43], v[42:43], v[130:131]
	v_add_co_u32_e32 v62, vcc, s0, v146
	s_mov_b32 s0, 0xfc090000
	s_nop 0
	v_addc_co_u32_e32 v63, vcc, -1, v147, vcc
	global_store_dwordx4 v[62:63], v[46:49], off offset:-3584 sc1
	global_store_dwordx4 v[62:63], v[42:45], off offset:-3520 sc1
	v_pk_mul_f32 v[32:33], v[32:33], v[136:137]
	v_add_co_u32_e32 v46, vcc, s0, v146
	v_pk_mul_f32 v[44:45], v[56:57], v[144:145]
	v_pk_mul_f32 v[42:43], v[54:55], v[142:143]
	v_addc_co_u32_e32 v47, vcc, -1, v147, vcc
	s_mov_b32 s0, 0xfc091000
	global_store_dwordx4 v[46:47], v[42:45], off sc1
	v_add_co_u32_e32 v46, vcc, s0, v146
	v_pk_mul_f32 v[30:31], v[30:31], v[134:135]
	s_nop 0
	v_addc_co_u32_e32 v47, vcc, -1, v147, vcc
	s_mov_b32 s0, 0xfc0a0000
	global_store_dwordx4 v[46:47], v[30:33], off offset:-3584 sc1
	v_pk_mul_f32 v[28:29], v[28:29], v[132:133]
	v_pk_mul_f32 v[26:27], v[26:27], v[130:131]
	v_add_co_u32_e32 v30, vcc, s0, v146
	global_store_dwordx4 v[46:47], v[26:29], off offset:-3520 sc1
	s_nop 0
	v_addc_co_u32_e32 v31, vcc, -1, v147, vcc
	v_pk_mul_f32 v[28:29], v[40:41], v[144:145]
	v_pk_mul_f32 v[26:27], v[38:39], v[142:143]
	s_mov_b32 s0, 0xfc0a1000
	global_store_dwordx4 v[30:31], v[26:29], off sc1
	v_add_co_u32_e32 v30, vcc, s0, v146
	v_pk_mul_f32 v[16:17], v[16:17], v[136:137]
	s_nop 0
	v_addc_co_u32_e32 v31, vcc, -1, v147, vcc
	v_pk_mul_f32 v[14:15], v[14:15], v[134:135]
	s_mov_b32 s0, 0xfc0b0000
	global_store_dwordx4 v[30:31], v[14:17], off offset:-3584 sc1
	v_pk_mul_f32 v[12:13], v[12:13], v[132:133]
	v_pk_mul_f32 v[10:11], v[10:11], v[130:131]
	v_add_co_u32_e32 v14, vcc, s0, v146
	global_store_dwordx4 v[30:31], v[10:13], off offset:-3520 sc1
	s_nop 0
	v_addc_co_u32_e32 v15, vcc, -1, v147, vcc
	v_pk_mul_f32 v[12:13], v[24:25], v[144:145]
	v_pk_mul_f32 v[10:11], v[22:23], v[142:143]
	s_mov_b32 s0, 0xfc0b1000
	global_store_dwordx4 v[14:15], v[10:13], off sc1
	v_add_co_u32_e32 v14, vcc, s0, v146
	v_pk_mul_f32 v[128:129], v[128:129], v[144:145]
	v_pk_mul_f32 v[126:127], v[126:127], v[142:143]
	v_pk_mul_f32 v[124:125], v[124:125], v[140:141]
	v_pk_mul_f32 v[122:123], v[122:123], v[138:139]
	v_pk_mul_f32 v[108:109], v[108:109], v[140:141]
	v_pk_mul_f32 v[106:107], v[106:107], v[138:139]
	v_pk_mul_f32 v[92:93], v[92:93], v[140:141]
	v_pk_mul_f32 v[90:91], v[90:91], v[138:139]
	v_pk_mul_f32 v[76:77], v[76:77], v[140:141]
	v_pk_mul_f32 v[74:75], v[74:75], v[138:139]
	v_pk_mul_f32 v[72:73], v[72:73], v[136:137]
	v_pk_mul_f32 v[70:71], v[70:71], v[134:135]
	v_pk_mul_f32 v[60:61], v[60:61], v[140:141]
	v_pk_mul_f32 v[58:59], v[58:59], v[138:139]
	v_pk_mul_f32 v[44:45], v[52:53], v[140:141]
	v_pk_mul_f32 v[42:43], v[50:51], v[138:139]
	v_pk_mul_f32 v[28:29], v[36:37], v[140:141]
	v_pk_mul_f32 v[26:27], v[34:35], v[138:139]
	v_pk_mul_f32 v[12:13], v[20:21], v[140:141]
	v_pk_mul_f32 v[10:11], v[18:19], v[138:139]
	v_addc_co_u32_e32 v15, vcc, -1, v147, vcc
	v_pk_mul_f32 v[8:9], v[8:9], v[136:137]
	v_pk_mul_f32 v[6:7], v[6:7], v[134:135]
	v_pk_mul_f32 v[4:5], v[4:5], v[132:133]
	v_pk_mul_f32 v[2:3], v[2:3], v[130:131]
	global_store_dwordx4 v[150:151], v[126:129], off sc1
	global_store_dwordx4 v[148:149], v[122:125], off offset:64 sc1
	global_store_dwordx4 v[110:111], v[106:109], off offset:-4032 sc1
	global_store_dwordx4 v[94:95], v[90:93], off offset:-4032 sc1
	global_store_dwordx4 v[78:79], v[74:77], off offset:-4032 sc1
	global_store_dwordx4 v[78:79], v[70:73], off offset:-3584 sc1
	global_store_dwordx4 v[62:63], v[58:61], off offset:-4032 sc1
	global_store_dwordx4 v[46:47], v[42:45], off offset:-4032 sc1
	global_store_dwordx4 v[30:31], v[26:29], off offset:-4032 sc1
	global_store_dwordx4 v[14:15], v[10:13], off offset:-4032 sc1
	global_store_dwordx4 v[14:15], v[6:9], off offset:-3584 sc1
	global_store_dwordx4 v[14:15], v[2:5], off offset:-3520 sc1

.Lfold_bdone:
	s_lshl_b64 s[8:9], s[14:15], 12
	v_lshl_add_u64 v[40:41], v[34:35], 0, s[8:9]
	global_store_dwordx4 v[40:41], v[30:33], off sc1
	global_store_dwordx4 v[40:41], v[26:29], off offset:1024 sc1
	global_store_dwordx4 v[40:41], v[22:25], off offset:2048 sc1
	global_store_dwordx4 v[40:41], v[18:21], off offset:3072 sc1
	s_branch .LBB0_1101

.LBB0_1174:
	v_mul_f32_e32 v151, 0xbfb8aa3b, v126
	v_exp_f32_e32 v151, v151
	v_readlane_b32 s0, v250, 13
	v_lshl_or_b32 v142, s2, 7, v148
	v_readlane_b32 s1, v250, 14
	v_add_f32_e32 v151, 1.0, v151
	v_rcp_f32_e32 v151, v151
	v_lshl_add_u32 v150, s4, 8, v146
	v_ashrrev_i32_e32 v143, 31, v142
	v_mov_b64_e32 v[140:141], s[0:1]
	v_mul_f32_e32 v126, v126, v151
	v_mul_f32_e32 v122, v126, v122
	v_mul_f32_e32 v126, 0xbfb8aa3b, v127
	v_exp_f32_e32 v126, v126
	s_movk_i32 s2, 0x1600
	v_mad_i64_i32 v[144:145], s[0:1], v150, s2, v[140:141]
	v_add_f32_e32 v126, 1.0, v126
	v_rcp_f32_e32 v126, v126
	v_lshlrev_b64 v[142:143], 1, v[142:143]
	v_lshl_add_u64 v[144:145], v[144:145], 0, v[142:143]
	v_readlane_b32 s18, v249, 56
	v_mul_f32_e32 v126, v127, v126
	v_mul_f32_e32 v123, v126, v123
	v_cvt_pk_bf16_f32 v122, v122, v123
	v_mul_f32_e32 v123, 0xbfb8aa3b, v128
	v_exp_f32_e32 v123, v123
	s_andn2_b64 vcc, exec, s[38:39]
	v_readlane_b32 s19, v249, 57
	v_add_f32_e32 v123, 1.0, v123
	v_rcp_f32_e32 v123, v123
	s_nop 0
	v_mul_f32_e32 v123, v128, v123
	v_mul_f32_e32 v123, v123, v124
	v_mul_f32_e32 v124, 0xbfb8aa3b, v129
	v_exp_f32_e32 v124, v124
	s_nop 0
	v_add_f32_e32 v124, 1.0, v124
	v_rcp_f32_e32 v124, v124
	s_nop 0
	v_mul_f32_e32 v124, v129, v124
	v_mul_f32_e32 v124, v124, v125
	v_cvt_pk_bf16_f32 v123, v123, v124
	v_mul_f32_e32 v124, 0xbfb8aa3b, v118
	v_exp_f32_e32 v124, v124
	s_nop 0
	v_add_f32_e32 v124, 1.0, v124
	v_rcp_f32_e32 v124, v124
	s_nop 0
	v_mul_f32_e32 v118, v118, v124
	v_mul_f32_e32 v114, v118, v114
	v_mul_f32_e32 v118, 0xbfb8aa3b, v119
	v_exp_f32_e32 v118, v118
	s_nop 0
	v_add_f32_e32 v118, 1.0, v118
	v_rcp_f32_e32 v118, v118
	s_nop 0
	v_mul_f32_e32 v118, v119, v118
	v_mul_f32_e32 v115, v118, v115
	v_cvt_pk_bf16_f32 v124, v114, v115
	v_mul_f32_e32 v114, 0xbfb8aa3b, v120
	v_exp_f32_e32 v114, v114
	v_mul_f32_e32 v115, 0xbfb8aa3b, v121
	v_exp_f32_e32 v115, v115
	v_add_f32_e32 v114, 1.0, v114
	v_rcp_f32_e32 v114, v114
	v_add_f32_e32 v115, 1.0, v115
	v_rcp_f32_e32 v115, v115
	v_mul_f32_e32 v114, v120, v114
	v_mul_f32_e32 v114, v114, v116
	v_mul_f32_e32 v116, 0xbfb8aa3b, v110
	v_exp_f32_e32 v116, v116
	v_mul_f32_e32 v115, v121, v115
	v_mul_f32_e32 v115, v115, v117
	v_cvt_pk_bf16_f32 v125, v114, v115
	v_add_f32_e32 v116, 1.0, v116
	v_rcp_f32_e32 v116, v116
	global_store_dwordx4 v[144:145], v[122:125], off sc1
	v_or_b32_e32 v114, 16, v150
	v_mad_i64_i32 v[114:115], s[0:1], v114, s2, v[140:141]
	v_mul_f32_e32 v110, v110, v116
	v_mul_f32_e32 v106, v110, v106
	v_mul_f32_e32 v110, 0xbfb8aa3b, v111
	v_exp_f32_e32 v110, v110
	v_lshl_add_u64 v[114:115], v[114:115], 0, v[142:143]
	v_add_f32_e32 v110, 1.0, v110
	v_rcp_f32_e32 v110, v110
	s_nop 0
	v_mul_f32_e32 v110, v111, v110
	v_mul_f32_e32 v107, v110, v107
	v_cvt_pk_bf16_f32 v106, v106, v107
	v_mul_f32_e32 v107, 0xbfb8aa3b, v112
	v_exp_f32_e32 v107, v107
	s_nop 0
	v_add_f32_e32 v107, 1.0, v107
	v_rcp_f32_e32 v107, v107
	s_nop 0
	v_mul_f32_e32 v107, v112, v107
	v_mul_f32_e32 v107, v107, v108
	v_mul_f32_e32 v108, 0xbfb8aa3b, v113
	v_exp_f32_e32 v108, v108
	s_nop 0
	v_add_f32_e32 v108, 1.0, v108
	v_rcp_f32_e32 v108, v108
	s_nop 0
	v_mul_f32_e32 v108, v113, v108
	v_mul_f32_e32 v108, v108, v109
	v_cvt_pk_bf16_f32 v107, v107, v108
	v_mul_f32_e32 v108, 0xbfb8aa3b, v102
	v_exp_f32_e32 v108, v108
	s_nop 0
	v_add_f32_e32 v108, 1.0, v108
	v_rcp_f32_e32 v108, v108
	s_nop 0
	v_mul_f32_e32 v102, v102, v108
	v_mul_f32_e32 v98, v102, v98
	v_mul_f32_e32 v102, 0xbfb8aa3b, v103
	v_exp_f32_e32 v102, v102
	s_nop 0
	v_add_f32_e32 v102, 1.0, v102
	v_rcp_f32_e32 v102, v102
	s_nop 0
	v_mul_f32_e32 v102, v103, v102
	v_mul_f32_e32 v99, v102, v99
	v_cvt_pk_bf16_f32 v108, v98, v99
	v_mul_f32_e32 v98, 0xbfb8aa3b, v104
	v_exp_f32_e32 v98, v98
	v_mul_f32_e32 v99, 0xbfb8aa3b, v105
	v_exp_f32_e32 v99, v99
	v_add_f32_e32 v98, 1.0, v98
	v_rcp_f32_e32 v98, v98
	v_add_f32_e32 v99, 1.0, v99
	v_rcp_f32_e32 v99, v99
	v_mul_f32_e32 v98, v104, v98
	v_mul_f32_e32 v98, v98, v100
	v_mul_f32_e32 v100, 0xbfb8aa3b, v94
	v_exp_f32_e32 v100, v100
	v_mul_f32_e32 v99, v105, v99
	v_mul_f32_e32 v99, v99, v101
	v_cvt_pk_bf16_f32 v109, v98, v99
	v_add_f32_e32 v100, 1.0, v100
	v_rcp_f32_e32 v100, v100
	global_store_dwordx4 v[114:115], v[106:109], off sc1
	v_or_b32_e32 v98, 32, v150
	v_mad_i64_i32 v[98:99], s[0:1], v98, s2, v[140:141]
	v_mul_f32_e32 v94, v94, v100
	v_mul_f32_e32 v90, v94, v90
	v_mul_f32_e32 v94, 0xbfb8aa3b, v95
	v_exp_f32_e32 v94, v94
	v_lshl_add_u64 v[98:99], v[98:99], 0, v[142:143]
	v_add_f32_e32 v94, 1.0, v94
	v_rcp_f32_e32 v94, v94
	s_nop 0
	v_mul_f32_e32 v94, v95, v94
	v_mul_f32_e32 v91, v94, v91
	v_cvt_pk_bf16_f32 v90, v90, v91
	v_mul_f32_e32 v91, 0xbfb8aa3b, v96
	v_exp_f32_e32 v91, v91
	s_nop 0
	v_add_f32_e32 v91, 1.0, v91
	v_rcp_f32_e32 v91, v91
	s_nop 0
	v_mul_f32_e32 v91, v96, v91
	v_mul_f32_e32 v91, v91, v92
	v_mul_f32_e32 v92, 0xbfb8aa3b, v97
	v_exp_f32_e32 v92, v92
	s_nop 0
	v_add_f32_e32 v92, 1.0, v92
	v_rcp_f32_e32 v92, v92
	s_nop 0
	v_mul_f32_e32 v92, v97, v92
	v_mul_f32_e32 v92, v92, v93
	v_cvt_pk_bf16_f32 v91, v91, v92
	v_mul_f32_e32 v92, 0xbfb8aa3b, v86
	v_exp_f32_e32 v92, v92
	s_nop 0
	v_add_f32_e32 v92, 1.0, v92
	v_rcp_f32_e32 v92, v92
	s_nop 0
	v_mul_f32_e32 v86, v86, v92
	v_mul_f32_e32 v82, v86, v82
	v_mul_f32_e32 v86, 0xbfb8aa3b, v87
	v_exp_f32_e32 v86, v86
	s_nop 0
	v_add_f32_e32 v86, 1.0, v86
	v_rcp_f32_e32 v86, v86
	s_nop 0
	v_mul_f32_e32 v86, v87, v86
	v_mul_f32_e32 v83, v86, v83
	v_cvt_pk_bf16_f32 v92, v82, v83
	v_mul_f32_e32 v82, 0xbfb8aa3b, v88
	v_exp_f32_e32 v82, v82
	v_mul_f32_e32 v83, 0xbfb8aa3b, v89
	v_exp_f32_e32 v83, v83
	v_add_f32_e32 v82, 1.0, v82
	v_rcp_f32_e32 v82, v82
	v_add_f32_e32 v83, 1.0, v83
	v_rcp_f32_e32 v83, v83
	v_mul_f32_e32 v82, v88, v82
	v_mul_f32_e32 v82, v82, v84
	v_mul_f32_e32 v84, 0xbfb8aa3b, v78
	v_exp_f32_e32 v84, v84
	v_mul_f32_e32 v83, v89, v83
	v_mul_f32_e32 v83, v83, v85
	v_cvt_pk_bf16_f32 v93, v82, v83
	v_add_f32_e32 v84, 1.0, v84
	v_rcp_f32_e32 v84, v84
	global_store_dwordx4 v[98:99], v[90:93], off sc1
	v_or_b32_e32 v82, 48, v150
	v_mad_i64_i32 v[82:83], s[0:1], v82, s2, v[140:141]
	v_mul_f32_e32 v78, v78, v84
	v_mul_f32_e32 v74, v78, v74
	v_mul_f32_e32 v78, 0xbfb8aa3b, v79
	v_exp_f32_e32 v78, v78
	v_lshl_add_u64 v[82:83], v[82:83], 0, v[142:143]
	v_add_f32_e32 v78, 1.0, v78
	v_rcp_f32_e32 v78, v78
	s_nop 0
	v_mul_f32_e32 v78, v79, v78
	v_mul_f32_e32 v75, v78, v75
	v_cvt_pk_bf16_f32 v74, v74, v75
	v_mul_f32_e32 v75, 0xbfb8aa3b, v80
	v_exp_f32_e32 v75, v75
	s_nop 0
	v_add_f32_e32 v75, 1.0, v75
	v_rcp_f32_e32 v75, v75
	s_nop 0
	v_mul_f32_e32 v75, v80, v75
	v_mul_f32_e32 v75, v75, v76
	v_mul_f32_e32 v76, 0xbfb8aa3b, v81
	v_exp_f32_e32 v76, v76
	s_nop 0
	v_add_f32_e32 v76, 1.0, v76
	v_rcp_f32_e32 v76, v76
	s_nop 0
	v_mul_f32_e32 v76, v81, v76
	v_mul_f32_e32 v76, v76, v77
	v_cvt_pk_bf16_f32 v75, v75, v76
	v_mul_f32_e32 v76, 0xbfb8aa3b, v70
	v_exp_f32_e32 v76, v76
	s_nop 0
	v_add_f32_e32 v76, 1.0, v76
	v_rcp_f32_e32 v76, v76
	s_nop 0
	v_mul_f32_e32 v70, v70, v76
	v_mul_f32_e32 v66, v70, v66
	v_mul_f32_e32 v70, 0xbfb8aa3b, v71
	v_exp_f32_e32 v70, v70
	s_nop 0
	v_add_f32_e32 v70, 1.0, v70
	v_rcp_f32_e32 v70, v70
	s_nop 0
	v_mul_f32_e32 v70, v71, v70
	v_mul_f32_e32 v67, v70, v67
	v_cvt_pk_bf16_f32 v76, v66, v67
	v_mul_f32_e32 v66, 0xbfb8aa3b, v72
	v_exp_f32_e32 v66, v66
	v_mul_f32_e32 v67, 0xbfb8aa3b, v73
	v_exp_f32_e32 v67, v67
	v_add_f32_e32 v66, 1.0, v66
	v_rcp_f32_e32 v66, v66
	v_add_f32_e32 v67, 1.0, v67
	v_rcp_f32_e32 v67, v67
	v_mul_f32_e32 v66, v72, v66
	v_mul_f32_e32 v66, v66, v68
	v_mul_f32_e32 v68, 0xbfb8aa3b, v62
	v_exp_f32_e32 v68, v68
	v_mul_f32_e32 v67, v73, v67
	v_mul_f32_e32 v67, v67, v69
	v_cvt_pk_bf16_f32 v77, v66, v67
	v_add_f32_e32 v68, 1.0, v68
	v_rcp_f32_e32 v68, v68
	global_store_dwordx4 v[82:83], v[74:77], off sc1
	v_add_u32_e32 v66, 0x80, v150
	v_mad_i64_i32 v[66:67], s[0:1], v66, s2, v[140:141]
	v_mul_f32_e32 v62, v62, v68
	v_mul_f32_e32 v58, v62, v58
	v_mul_f32_e32 v62, 0xbfb8aa3b, v63
	v_exp_f32_e32 v62, v62
	v_lshl_add_u64 v[66:67], v[66:67], 0, v[142:143]
	v_add_f32_e32 v62, 1.0, v62
	v_rcp_f32_e32 v62, v62
	s_nop 0
	v_mul_f32_e32 v62, v63, v62
	v_mul_f32_e32 v59, v62, v59
	v_cvt_pk_bf16_f32 v58, v58, v59
	v_mul_f32_e32 v59, 0xbfb8aa3b, v64
	v_exp_f32_e32 v59, v59
	s_nop 0
	v_add_f32_e32 v59, 1.0, v59
	v_rcp_f32_e32 v59, v59
	s_nop 0
	v_mul_f32_e32 v59, v64, v59
	v_mul_f32_e32 v59, v59, v60
	v_mul_f32_e32 v60, 0xbfb8aa3b, v65
	v_exp_f32_e32 v60, v60
	s_nop 0
	v_add_f32_e32 v60, 1.0, v60
	v_rcp_f32_e32 v60, v60
	s_nop 0
	v_mul_f32_e32 v60, v65, v60
	v_mul_f32_e32 v60, v60, v61
	v_cvt_pk_bf16_f32 v59, v59, v60
	v_mul_f32_e32 v60, 0xbfb8aa3b, v54
	v_exp_f32_e32 v60, v60
	s_nop 0
	v_add_f32_e32 v60, 1.0, v60
	v_rcp_f32_e32 v60, v60
	s_nop 0
	v_mul_f32_e32 v54, v54, v60
	v_mul_f32_e32 v50, v54, v50
	v_mul_f32_e32 v54, 0xbfb8aa3b, v55
	v_exp_f32_e32 v54, v54
	s_nop 0
	v_add_f32_e32 v54, 1.0, v54
	v_rcp_f32_e32 v54, v54
	s_nop 0
	v_mul_f32_e32 v54, v55, v54
	v_mul_f32_e32 v51, v54, v51
	v_cvt_pk_bf16_f32 v60, v50, v51
	v_mul_f32_e32 v50, 0xbfb8aa3b, v56
	v_exp_f32_e32 v50, v50
	v_mul_f32_e32 v51, 0xbfb8aa3b, v57
	v_exp_f32_e32 v51, v51
	v_add_f32_e32 v50, 1.0, v50
	v_rcp_f32_e32 v50, v50
	v_add_f32_e32 v51, 1.0, v51
	v_rcp_f32_e32 v51, v51
	v_mul_f32_e32 v50, v56, v50
	v_mul_f32_e32 v50, v50, v52
	v_mul_f32_e32 v52, 0xbfb8aa3b, v46
	v_exp_f32_e32 v52, v52
	v_mul_f32_e32 v51, v57, v51
	v_mul_f32_e32 v51, v51, v53
	v_cvt_pk_bf16_f32 v61, v50, v51
	v_add_f32_e32 v52, 1.0, v52
	v_rcp_f32_e32 v52, v52
	global_store_dwordx4 v[66:67], v[58:61], off sc1
	v_add_u32_e32 v50, 0x90, v150
	v_mad_i64_i32 v[50:51], s[0:1], v50, s2, v[140:141]
	v_mul_f32_e32 v46, v46, v52
	v_mul_f32_e32 v42, v46, v42
	v_mul_f32_e32 v46, 0xbfb8aa3b, v47
	v_exp_f32_e32 v46, v46
	v_lshl_add_u64 v[50:51], v[50:51], 0, v[142:143]
	v_add_f32_e32 v46, 1.0, v46
	v_rcp_f32_e32 v46, v46
	s_nop 0
	v_mul_f32_e32 v46, v47, v46
	v_mul_f32_e32 v43, v46, v43
	v_cvt_pk_bf16_f32 v42, v42, v43
	v_mul_f32_e32 v43, 0xbfb8aa3b, v48
	v_exp_f32_e32 v43, v43
	s_nop 0
	v_add_f32_e32 v43, 1.0, v43
	v_rcp_f32_e32 v43, v43
	s_nop 0
	v_mul_f32_e32 v43, v48, v43
	v_mul_f32_e32 v43, v43, v44
	v_mul_f32_e32 v44, 0xbfb8aa3b, v49
	v_exp_f32_e32 v44, v44
	s_nop 0
	v_add_f32_e32 v44, 1.0, v44
	v_rcp_f32_e32 v44, v44
	s_nop 0
	v_mul_f32_e32 v44, v49, v44
	v_mul_f32_e32 v44, v44, v45
	v_cvt_pk_bf16_f32 v43, v43, v44
	v_mul_f32_e32 v44, 0xbfb8aa3b, v38
	v_exp_f32_e32 v44, v44
	s_nop 0
	v_add_f32_e32 v44, 1.0, v44
	v_rcp_f32_e32 v44, v44
	s_nop 0
	v_mul_f32_e32 v38, v38, v44
	v_mul_f32_e32 v34, v38, v34
	v_mul_f32_e32 v38, 0xbfb8aa3b, v39
	v_exp_f32_e32 v38, v38
	s_nop 0
	v_add_f32_e32 v38, 1.0, v38
	v_rcp_f32_e32 v38, v38
	s_nop 0
	v_mul_f32_e32 v38, v39, v38
	v_mul_f32_e32 v35, v38, v35
	v_cvt_pk_bf16_f32 v44, v34, v35
	v_mul_f32_e32 v34, 0xbfb8aa3b, v40
	v_exp_f32_e32 v34, v34
	v_mul_f32_e32 v35, 0xbfb8aa3b, v41
	v_exp_f32_e32 v35, v35
	v_add_f32_e32 v34, 1.0, v34
	v_rcp_f32_e32 v34, v34
	v_add_f32_e32 v35, 1.0, v35
	v_rcp_f32_e32 v35, v35
	v_mul_f32_e32 v34, v40, v34
	v_mul_f32_e32 v34, v34, v36
	v_mul_f32_e32 v36, 0xbfb8aa3b, v30
	v_exp_f32_e32 v36, v36
	v_mul_f32_e32 v35, v41, v35
	v_mul_f32_e32 v35, v35, v37
	v_cvt_pk_bf16_f32 v45, v34, v35
	v_add_f32_e32 v36, 1.0, v36
	v_rcp_f32_e32 v36, v36
	global_store_dwordx4 v[50:51], v[42:45], off sc1
	v_add_u32_e32 v34, 0xa0, v150
	v_mad_i64_i32 v[34:35], s[0:1], v34, s2, v[140:141]
	v_mul_f32_e32 v30, v30, v36
	v_mul_f32_e32 v26, v30, v26
	v_mul_f32_e32 v30, 0xbfb8aa3b, v31
	v_exp_f32_e32 v30, v30
	v_lshl_add_u64 v[34:35], v[34:35], 0, v[142:143]
	v_add_f32_e32 v30, 1.0, v30
	v_rcp_f32_e32 v30, v30
	s_nop 0
	v_mul_f32_e32 v30, v31, v30
	v_mul_f32_e32 v27, v30, v27
	v_cvt_pk_bf16_f32 v26, v26, v27
	v_mul_f32_e32 v27, 0xbfb8aa3b, v32
	v_exp_f32_e32 v27, v27
	s_nop 0
	v_add_f32_e32 v27, 1.0, v27
	v_rcp_f32_e32 v27, v27
	s_nop 0
	v_mul_f32_e32 v27, v32, v27
	v_mul_f32_e32 v27, v27, v28
	v_mul_f32_e32 v28, 0xbfb8aa3b, v33
	v_exp_f32_e32 v28, v28
	s_nop 0
	v_add_f32_e32 v28, 1.0, v28
	v_rcp_f32_e32 v28, v28
	s_nop 0
	v_mul_f32_e32 v28, v33, v28
	v_mul_f32_e32 v28, v28, v29
	v_cvt_pk_bf16_f32 v27, v27, v28
	v_mul_f32_e32 v28, 0xbfb8aa3b, v22
	v_exp_f32_e32 v28, v28
	s_nop 0
	v_add_f32_e32 v28, 1.0, v28
	v_rcp_f32_e32 v28, v28
	s_nop 0
	v_mul_f32_e32 v22, v22, v28
	v_mul_f32_e32 v18, v22, v18
	v_mul_f32_e32 v22, 0xbfb8aa3b, v23
	v_exp_f32_e32 v22, v22
	s_nop 0
	v_add_f32_e32 v22, 1.0, v22
	v_rcp_f32_e32 v22, v22
	s_nop 0
	v_mul_f32_e32 v22, v23, v22
	v_mul_f32_e32 v19, v22, v19
	v_cvt_pk_bf16_f32 v28, v18, v19
	v_mul_f32_e32 v18, 0xbfb8aa3b, v24
	v_exp_f32_e32 v18, v18
	v_mul_f32_e32 v19, 0xbfb8aa3b, v25
	v_exp_f32_e32 v19, v19
	v_add_f32_e32 v18, 1.0, v18
	v_rcp_f32_e32 v18, v18
	v_add_f32_e32 v19, 1.0, v19
	v_rcp_f32_e32 v19, v19
	v_mul_f32_e32 v18, v24, v18
	v_mul_f32_e32 v18, v18, v20
	v_mul_f32_e32 v20, 0xbfb8aa3b, v14
	v_exp_f32_e32 v20, v20
	v_mul_f32_e32 v19, v25, v19
	v_mul_f32_e32 v19, v19, v21
	v_cvt_pk_bf16_f32 v29, v18, v19
	v_add_f32_e32 v20, 1.0, v20
	v_rcp_f32_e32 v20, v20
	global_store_dwordx4 v[34:35], v[26:29], off sc1
	v_add_u32_e32 v18, 0xb0, v150
	v_mad_i64_i32 v[18:19], s[0:1], v18, s2, v[140:141]
	v_mul_f32_e32 v14, v14, v20
	v_mul_f32_e32 v10, v14, v10
	v_mul_f32_e32 v14, 0xbfb8aa3b, v15
	v_exp_f32_e32 v14, v14
	v_lshl_add_u64 v[18:19], v[18:19], 0, v[142:143]
	s_mov_b64 s[0:1], -1
	v_add_f32_e32 v14, 1.0, v14
	v_rcp_f32_e32 v14, v14
	s_nop 0
	v_mul_f32_e32 v14, v15, v14
	v_mul_f32_e32 v11, v14, v11
	v_cvt_pk_bf16_f32 v10, v10, v11
	v_mul_f32_e32 v11, 0xbfb8aa3b, v16
	v_exp_f32_e32 v11, v11
	s_nop 0
	v_add_f32_e32 v11, 1.0, v11
	v_rcp_f32_e32 v11, v11
	s_nop 0
	v_mul_f32_e32 v11, v16, v11
	v_mul_f32_e32 v11, v11, v12
	v_mul_f32_e32 v12, 0xbfb8aa3b, v17
	v_exp_f32_e32 v12, v12
	s_nop 0
	v_add_f32_e32 v12, 1.0, v12
	v_rcp_f32_e32 v12, v12
	s_nop 0
	v_mul_f32_e32 v12, v17, v12
	v_mul_f32_e32 v12, v12, v13
	v_cvt_pk_bf16_f32 v11, v11, v12
	v_mul_f32_e32 v12, 0xbfb8aa3b, v6
	v_exp_f32_e32 v12, v12
	s_nop 0
	v_add_f32_e32 v12, 1.0, v12
	v_rcp_f32_e32 v12, v12
	s_nop 0
	v_mul_f32_e32 v6, v6, v12
	v_mul_f32_e32 v2, v6, v2
	v_mul_f32_e32 v6, 0xbfb8aa3b, v7
	v_exp_f32_e32 v6, v6
	s_nop 0
	v_add_f32_e32 v6, 1.0, v6
	v_rcp_f32_e32 v6, v6
	s_nop 0
	v_mul_f32_e32 v6, v7, v6
	v_mul_f32_e32 v3, v6, v3
	v_cvt_pk_bf16_f32 v12, v2, v3
	v_mul_f32_e32 v2, 0xbfb8aa3b, v8
	v_mul_f32_e32 v3, 0xbfb8aa3b, v9
	v_exp_f32_e32 v2, v2
	v_exp_f32_e32 v3, v3
	v_add_f32_e32 v2, 1.0, v2
	v_add_f32_e32 v3, 1.0, v3
	v_rcp_f32_e32 v2, v2
	v_rcp_f32_e32 v3, v3
	v_mul_f32_e32 v2, v8, v2
	v_mul_f32_e32 v3, v9, v3
	v_mul_f32_e32 v2, v2, v4
	v_mul_f32_e32 v3, v3, v5
	v_cvt_pk_bf16_f32 v13, v2, v3
	global_store_dwordx4 v[18:19], v[10:13], off sc1
	s_cbranch_vccnz .LBB0_1163
	s_andn2_b64 vcc, exec, s[40:41]
	s_cbranch_vccnz .LBB0_1162
	s_barrier
	s_branch .LBB0_1162

.LBB0_1270:
	v_lshlrev_b32_e32 v0, 2, v133
	v_lshl_or_b32 v0, s36, 8, v0
	s_lshl_b32 s0, s14, 2
	v_readlane_b32 s1, v254, 46
	v_or_b32_e32 v130, s31, v0
	s_add_u32 s0, s1, s0
	v_readlane_b32 s1, v254, 48
	v_ashrrev_i32_e32 v131, 31, v130
	s_addc_u32 s1, s1, 0
	v_lshlrev_b64 v[130:131], 2, v[130:131]
	v_lshl_add_u64 v[142:143], s[0:1], 0, v[130:131]
	s_barrier
	global_load_dwordx4 v[134:137], v[142:143], off
	global_load_dwordx4 v[138:141], v[142:143], off offset:64
	global_load_dwordx4 v[148:151], v[142:143], off offset:512
	global_load_dwordx4 v[152:155], v[142:143], off offset:576
	s_ashr_i32 s5, s4, 31
	s_ashr_i32 s7, s6, 31
	s_lshl_b64 s[0:1], s[6:7], 20
	s_lshl_b64 s[2:3], s[4:5], 21
	v_readlane_b32 s4, v251, 39
	v_readlane_b32 s5, v251, 40
	s_add_u32 s0, s4, s0
	s_addc_u32 s1, s5, s1
	s_add_u32 s0, s0, s2
	s_addc_u32 s1, s1, s3
	s_ashr_i32 s2, s12, 31
	v_or_b32_e32 v132, s12, v132
	v_mov_b32_e32 v133, s2
	v_lshlrev_b64 v[132:133], 12, v[132:133]
	v_lshl_add_u64 v[132:133], s[0:1], 0, v[132:133]
	s_brev_b32 s0, 63
	v_lshl_add_u64 v[130:131], v[132:133], 0, v[130:131]
	s_mov_b32 s1, -1
	v_lshl_add_u64 v[156:157], v[130:131], 0, s[0:1]
	s_brev_b32 s0, 63
	v_add_co_u32_e32 v158, vcc, s0, v130
	s_mov_b32 s0, 0xfc010000
	s_nop 0
	v_addc_co_u32_e32 v159, vcc, -1, v131, vcc
	v_add_co_u32_e32 v160, vcc, s0, v130
	s_mov_b32 s0, 0xfc011000
	s_nop 0
	v_addc_co_u32_e32 v161, vcc, -1, v131, vcc
	v_add_co_u32_e32 v162, vcc, s0, v130
	s_mov_b32 s0, 0xfc020000
	s_nop 0
	v_addc_co_u32_e32 v163, vcc, -1, v131, vcc
	v_add_co_u32_e32 v164, vcc, s0, v130
	s_mov_b32 s0, 0xfc021000
	s_nop 0
	v_addc_co_u32_e32 v165, vcc, -1, v131, vcc
	v_add_co_u32_e32 v166, vcc, s0, v130
	s_mov_b32 s0, 0xfc030000
	s_nop 0
	v_addc_co_u32_e32 v167, vcc, -1, v131, vcc
	v_readlane_b32 s30, v254, 4
	v_readlane_b32 s34, v254, 6
	v_readlane_b32 s31, v254, 5
	v_readlane_b32 s35, v254, 7
	s_waitcnt vmcnt(0)
	v_pk_mul_f32 v[146:147], v[136:137], 0.5 op_sel_hi:[1,0]
	v_pk_mul_f32 v[144:145], v[134:135], 0.5 op_sel_hi:[1,0]
	v_pk_mul_f32 v[136:137], v[148:149], 0.5 op_sel_hi:[1,0]
	v_pk_mul_f32 v[142:143], v[140:141], 0.5 op_sel_hi:[1,0]
	v_pk_mul_f32 v[140:141], v[138:139], 0.5 op_sel_hi:[1,0]
	v_pk_mul_f32 v[138:139], v[150:151], 0.5 op_sel_hi:[1,0]
	v_pk_mul_f32 v[134:135], v[154:155], 0.5 op_sel_hi:[1,0]
	v_pk_mul_f32 v[132:133], v[152:153], 0.5 op_sel_hi:[1,0]
	v_pk_mul_f32 v[128:129], v[128:129], v[146:147]
	v_pk_mul_f32 v[126:127], v[126:127], v[144:145]
	v_pk_mul_f32 v[82:83], v[82:83], v[136:137]
	v_pk_mul_f32 v[124:125], v[124:125], v[142:143]
	v_pk_mul_f32 v[122:123], v[122:123], v[140:141]
	v_pk_mul_f32 v[104:105], v[104:105], v[138:139]
	v_pk_mul_f32 v[102:103], v[102:103], v[136:137]
	v_pk_mul_f32 v[100:101], v[100:101], v[134:135]
	v_pk_mul_f32 v[98:99], v[98:99], v[132:133]
	v_pk_mul_f32 v[120:121], v[120:121], v[146:147]
	v_pk_mul_f32 v[118:119], v[118:119], v[144:145]
	v_pk_mul_f32 v[116:117], v[116:117], v[142:143]
	v_pk_mul_f32 v[114:115], v[114:115], v[140:141]
	v_pk_mul_f32 v[96:97], v[96:97], v[138:139]
	v_pk_mul_f32 v[94:95], v[94:95], v[136:137]
	v_pk_mul_f32 v[92:93], v[92:93], v[134:135]
	v_pk_mul_f32 v[90:91], v[90:91], v[132:133]
	v_pk_mul_f32 v[112:113], v[112:113], v[146:147]
	v_pk_mul_f32 v[110:111], v[110:111], v[144:145]
	v_pk_mul_f32 v[108:109], v[108:109], v[142:143]
	v_pk_mul_f32 v[106:107], v[106:107], v[140:141]
	v_pk_mul_f32 v[84:85], v[84:85], v[138:139]
	global_store_dwordx4 v[158:159], v[126:129], off sc1
	global_store_dwordx4 v[156:157], v[122:125], off offset:64 sc1
	global_store_dwordx4 v[156:157], v[102:105], off offset:512 sc1
	global_store_dwordx4 v[156:157], v[98:101], off offset:576 sc1
	global_store_dwordx4 v[160:161], v[118:121], off sc1
	global_store_dwordx4 v[162:163], v[114:117], off offset:-4032 sc1
	global_store_dwordx4 v[162:163], v[94:97], off offset:-3584 sc1
	global_store_dwordx4 v[162:163], v[90:93], off offset:-3520 sc1
	global_store_dwordx4 v[164:165], v[110:113], off sc1
	global_store_dwordx4 v[166:167], v[106:109], off offset:-4032 sc1
	global_store_dwordx4 v[166:167], v[82:85], off offset:-3584 sc1
	v_pk_mul_f32 v[76:77], v[76:77], v[134:135]
	v_pk_mul_f32 v[74:75], v[74:75], v[132:133]
	v_add_co_u32_e32 v82, vcc, s0, v130
	global_store_dwordx4 v[166:167], v[74:77], off offset:-3520 sc1
	s_nop 0
	v_addc_co_u32_e32 v83, vcc, -1, v131, vcc
	v_pk_mul_f32 v[76:77], v[88:89], v[146:147]
	v_pk_mul_f32 v[74:75], v[86:87], v[144:145]
	s_mov_b32 s0, 0xfc031000
	global_store_dwordx4 v[82:83], v[74:77], off sc1
	v_pk_mul_f32 v[68:69], v[68:69], v[134:135]
	v_pk_mul_f32 v[66:67], v[66:67], v[132:133]
	v_pk_mul_f32 v[74:75], v[78:79], v[140:141]
	v_add_co_u32_e32 v78, vcc, s0, v130
	s_mov_b32 s0, 0xfc080000
	s_nop 0
	v_addc_co_u32_e32 v79, vcc, -1, v131, vcc
	global_store_dwordx4 v[78:79], v[66:69], off offset:-3520 sc1
	v_pk_mul_f32 v[64:65], v[64:65], v[146:147]
	v_pk_mul_f32 v[62:63], v[62:63], v[144:145]
	v_add_co_u32_e32 v66, vcc, s0, v130
	s_mov_b32 s0, 0xfc081000
	s_nop 0
	v_addc_co_u32_e32 v67, vcc, -1, v131, vcc
	global_store_dwordx4 v[66:67], v[62:65], off sc1
	v_pk_mul_f32 v[48:49], v[48:49], v[138:139]
	v_pk_mul_f32 v[46:47], v[46:47], v[136:137]
	v_add_co_u32_e32 v62, vcc, s0, v130
	s_mov_b32 s0, 0xfc090000
	s_nop 0
	v_addc_co_u32_e32 v63, vcc, -1, v131, vcc
	global_store_dwordx4 v[62:63], v[46:49], off offset:-3584 sc1
	v_pk_mul_f32 v[44:45], v[44:45], v[134:135]
	v_pk_mul_f32 v[42:43], v[42:43], v[132:133]
	v_add_co_u32_e32 v46, vcc, s0, v130
	global_store_dwordx4 v[62:63], v[42:45], off offset:-3520 sc1
	s_nop 0
	v_addc_co_u32_e32 v47, vcc, -1, v131, vcc
	v_pk_mul_f32 v[44:45], v[56:57], v[146:147]
	v_pk_mul_f32 v[42:43], v[54:55], v[144:145]
	s_mov_b32 s0, 0xfc091000
	global_store_dwordx4 v[46:47], v[42:45], off sc1
	v_add_co_u32_e32 v46, vcc, s0, v130
	v_pk_mul_f32 v[32:33], v[32:33], v[138:139]
	s_nop 0
	v_addc_co_u32_e32 v47, vcc, -1, v131, vcc
	v_pk_mul_f32 v[30:31], v[30:31], v[136:137]
	s_mov_b32 s0, 0xfc0a0000
	global_store_dwordx4 v[46:47], v[30:33], off offset:-3584 sc1
	v_pk_mul_f32 v[28:29], v[28:29], v[134:135]
	v_pk_mul_f32 v[26:27], v[26:27], v[132:133]
	v_add_co_u32_e32 v30, vcc, s0, v130
	global_store_dwordx4 v[46:47], v[26:29], off offset:-3520 sc1
	s_nop 0
	v_addc_co_u32_e32 v31, vcc, -1, v131, vcc
	v_pk_mul_f32 v[28:29], v[40:41], v[146:147]
	v_pk_mul_f32 v[26:27], v[38:39], v[144:145]
	s_mov_b32 s0, 0xfc0a1000
	global_store_dwordx4 v[30:31], v[26:29], off sc1
	v_add_co_u32_e32 v30, vcc, s0, v130
	v_pk_mul_f32 v[16:17], v[16:17], v[138:139]
	s_nop 0
	v_addc_co_u32_e32 v31, vcc, -1, v131, vcc
	v_pk_mul_f32 v[14:15], v[14:15], v[136:137]
	s_mov_b32 s0, 0xfc0b0000
	global_store_dwordx4 v[30:31], v[14:17], off offset:-3584 sc1
	v_pk_mul_f32 v[12:13], v[12:13], v[134:135]
	v_pk_mul_f32 v[10:11], v[10:11], v[132:133]
	v_add_co_u32_e32 v14, vcc, s0, v130
	global_store_dwordx4 v[30:31], v[10:13], off offset:-3520 sc1
	s_nop 0
	v_addc_co_u32_e32 v15, vcc, -1, v131, vcc
	v_pk_mul_f32 v[12:13], v[24:25], v[146:147]
	v_pk_mul_f32 v[10:11], v[22:23], v[144:145]
	s_mov_b32 s0, 0xfc0b1000
	global_store_dwordx4 v[14:15], v[10:13], off sc1
	v_add_co_u32_e32 v14, vcc, s0, v130
	v_pk_mul_f32 v[76:77], v[80:81], v[142:143]
	v_pk_mul_f32 v[72:73], v[72:73], v[138:139]
	v_pk_mul_f32 v[70:71], v[70:71], v[136:137]
	v_pk_mul_f32 v[60:61], v[60:61], v[142:143]
	v_pk_mul_f32 v[58:59], v[58:59], v[140:141]
	v_pk_mul_f32 v[44:45], v[52:53], v[142:143]
	v_pk_mul_f32 v[42:43], v[50:51], v[140:141]
	v_pk_mul_f32 v[28:29], v[36:37], v[142:143]
	v_pk_mul_f32 v[26:27], v[34:35], v[140:141]
	v_pk_mul_f32 v[12:13], v[20:21], v[142:143]
	v_pk_mul_f32 v[10:11], v[18:19], v[140:141]
	v_addc_co_u32_e32 v15, vcc, -1, v131, vcc
	v_pk_mul_f32 v[8:9], v[8:9], v[138:139]
	v_pk_mul_f32 v[6:7], v[6:7], v[136:137]
	v_pk_mul_f32 v[4:5], v[4:5], v[134:135]
	v_pk_mul_f32 v[2:3], v[2:3], v[132:133]
	global_store_dwordx4 v[78:79], v[74:77], off offset:-4032 sc1
	global_store_dwordx4 v[78:79], v[70:73], off offset:-3584 sc1
	global_store_dwordx4 v[62:63], v[58:61], off offset:-4032 sc1
	global_store_dwordx4 v[46:47], v[42:45], off offset:-4032 sc1
	global_store_dwordx4 v[30:31], v[26:29], off offset:-4032 sc1
	global_store_dwordx4 v[14:15], v[10:13], off offset:-4032 sc1
	global_store_dwordx4 v[14:15], v[6:9], off offset:-3584 sc1
	global_store_dwordx4 v[14:15], v[2:5], off offset:-3520 sc1
